# P3 attention: counted waits instead of full drains; P2: biasup GEMV and pool-diff loops with all loads in flight
# speedup vs baseline: 1.0058x; 1.0058x over previous
.LBB0_725:
	v_readlane_b32 s1, v254, 35
	s_lshl_b32 s46, s1, 9
	v_add_u32_e32 v26, s46, v32
	s_mov_b32 s1, 0x40000
	v_cmp_gt_i32_e32 vcc, s1, v26
	s_and_saveexec_b64 s[2:3], vcc
	v_readlane_b32 s88, v254, 52
	v_readlane_b32 s90, v254, 51
	v_readlane_b32 s89, v254, 53
	s_cbranch_execz .LBB0_736
	v_and_b32_e32 v0, 0x7f, v32
	v_readlane_b32 s4, v254, 47
	v_bfe_u32 v4, v32, 5, 2
	v_lshlrev_b32_e32 v0, 4, v0
	v_mov_b32_e32 v1, 0
	v_readlane_b32 s5, v254, 48
	v_lshlrev_b32_e64 v27, v4, 2
	s_lshl_b32 s1, s88, 9
	s_mov_b32 s12, 0x3ffff
	v_lshl_add_u64 v[2:3], s[4:5], 0, v[0:1]
	s_mov_b64 s[14:15], 0
	s_mov_b32 s16, 0xffff9000
	s_mov_b32 s17, -1
	s_mov_b64 s[18:19], 0x2000
	s_mov_b64 s[20:21], 0xa000000
	v_cmp_eq_u32_e64 s[4:5], 2, v27
	v_cmp_eq_u32_e64 s[6:7], 4, v27
	v_cmp_eq_u32_e64 s[8:9], 8, v27
.Lpl_item:
	v_ashrrev_i32_e32 v7, 4, v26
	v_and_b32_e32 v6, -8, v7
	v_min_u32_e32 v28, v27, v6
	v_mov_b32_e32 v7, 0
	v_lshlrev_b64 v[16:17], 11, v[6:7]
	v_lshl_add_u64 v[16:17], v[2:3], 0, v[16:17]
	v_lshl_add_u64 v[160:161], v[16:17], 0, s[16:17]
	v_lshl_add_u64 v[162:163], v[160:161], 0, s[18:19]
	v_lshl_add_u64 v[164:165], v[162:163], 0, s[18:19]
	v_lshl_add_u64 v[166:167], v[164:165], 0, s[18:19]
	v_lshl_add_u64 v[168:169], v[166:167], 0, s[18:19]
	v_lshl_add_u64 v[170:171], v[168:169], 0, s[18:19]
	v_lshl_add_u64 v[172:173], v[168:169], 0, s[20:21]
	v_lshl_add_u64 v[174:175], v[170:171], 0, s[20:21]
	v_mov_b32_e32 v64, 0
	v_mov_b32_e32 v65, 0
	v_mov_b32_e32 v66, 0
	v_mov_b32_e32 v67, 0
	v_mov_b32_e32 v68, 0
	v_mov_b32_e32 v69, 0
	v_mov_b32_e32 v70, 0
	v_mov_b32_e32 v71, 0
	v_mov_b32_e32 v72, 0
	v_mov_b32_e32 v73, 0
	v_mov_b32_e32 v74, 0
	v_mov_b32_e32 v75, 0
	v_mov_b32_e32 v76, 0
	v_mov_b32_e32 v77, 0
	v_mov_b32_e32 v78, 0
	v_mov_b32_e32 v79, 0
	v_mov_b32_e32 v80, 0
	v_mov_b32_e32 v81, 0
	v_mov_b32_e32 v82, 0
	v_mov_b32_e32 v83, 0
	v_mov_b32_e32 v84, 0
	v_mov_b32_e32 v85, 0
	v_mov_b32_e32 v86, 0
	v_mov_b32_e32 v87, 0
	v_mov_b32_e32 v88, 0
	v_mov_b32_e32 v89, 0
	v_mov_b32_e32 v90, 0
	v_mov_b32_e32 v91, 0
	v_mov_b32_e32 v92, 0
	v_mov_b32_e32 v93, 0
	v_mov_b32_e32 v94, 0
	v_mov_b32_e32 v95, 0
	v_mov_b32_e32 v96, 0
	v_mov_b32_e32 v97, 0
	v_mov_b32_e32 v98, 0
	v_mov_b32_e32 v99, 0
	v_mov_b32_e32 v100, 0
	v_mov_b32_e32 v101, 0
	v_mov_b32_e32 v102, 0
	v_mov_b32_e32 v103, 0
	v_mov_b32_e32 v104, 0
	v_mov_b32_e32 v105, 0
	v_mov_b32_e32 v106, 0
	v_mov_b32_e32 v107, 0
	v_mov_b32_e32 v108, 0
	v_mov_b32_e32 v109, 0
	v_mov_b32_e32 v110, 0
	v_mov_b32_e32 v111, 0
	v_mov_b32_e32 v112, 0
	v_mov_b32_e32 v113, 0
	v_mov_b32_e32 v114, 0
	v_mov_b32_e32 v115, 0
	v_mov_b32_e32 v116, 0
	v_mov_b32_e32 v117, 0
	v_mov_b32_e32 v118, 0
	v_mov_b32_e32 v119, 0
	v_mov_b32_e32 v120, 0
	v_mov_b32_e32 v121, 0
	v_mov_b32_e32 v122, 0
	v_mov_b32_e32 v123, 0
	v_mov_b32_e32 v124, 0
	v_mov_b32_e32 v125, 0
	v_mov_b32_e32 v126, 0
	v_mov_b32_e32 v127, 0
	global_load_dwordx4 v[128:131], v[168:169], off offset:-4096
	global_load_dwordx4 v[132:135], v[168:169], off offset:-2048
	global_load_dwordx4 v[136:139], v[168:169], off
	global_load_dwordx4 v[140:143], v[168:169], off offset:2048
	global_load_dwordx4 v[144:147], v[170:171], off offset:-4096
	global_load_dwordx4 v[148:151], v[170:171], off offset:-2048
	global_load_dwordx4 v[152:155], v[170:171], off
	global_load_dwordx4 v[156:159], v[170:171], off offset:2048
	v_cmp_le_u32_e32 vcc, 1, v28
	s_and_saveexec_b64 s[10:11], vcc
	global_load_dwordx4 v[64:67], v[166:167], off offset:2048
	s_mov_b64 exec, s[10:11]
	v_cmp_le_u32_e32 vcc, 2, v28
	s_and_saveexec_b64 s[10:11], vcc
	global_load_dwordx4 v[68:71], v[166:167], off
	s_mov_b64 exec, s[10:11]
	v_cmp_le_u32_e32 vcc, 3, v28
	s_and_saveexec_b64 s[10:11], vcc
	global_load_dwordx4 v[72:75], v[166:167], off offset:-2048
	s_mov_b64 exec, s[10:11]
	v_cmp_le_u32_e32 vcc, 4, v28
	s_and_saveexec_b64 s[10:11], vcc
	global_load_dwordx4 v[76:79], v[166:167], off offset:-4096
	s_mov_b64 exec, s[10:11]
	v_cmp_le_u32_e32 vcc, 5, v28
	s_and_saveexec_b64 s[10:11], vcc
	global_load_dwordx4 v[80:83], v[164:165], off offset:2048
	s_mov_b64 exec, s[10:11]
	v_cmp_le_u32_e32 vcc, 6, v28
	s_and_saveexec_b64 s[10:11], vcc
	global_load_dwordx4 v[84:87], v[164:165], off
	s_mov_b64 exec, s[10:11]
	v_cmp_le_u32_e32 vcc, 7, v28
	s_and_saveexec_b64 s[10:11], vcc
	global_load_dwordx4 v[88:91], v[164:165], off offset:-2048
	s_mov_b64 exec, s[10:11]
	v_cmp_le_u32_e32 vcc, 8, v28
	s_and_saveexec_b64 s[10:11], vcc
	global_load_dwordx4 v[92:95], v[164:165], off offset:-4096
	s_mov_b64 exec, s[10:11]
	v_cmp_le_u32_e32 vcc, 9, v28
	s_and_saveexec_b64 s[10:11], vcc
	global_load_dwordx4 v[96:99], v[162:163], off offset:2048
	s_mov_b64 exec, s[10:11]
	v_cmp_le_u32_e32 vcc, 10, v28
	s_and_saveexec_b64 s[10:11], vcc
	global_load_dwordx4 v[100:103], v[162:163], off
	s_mov_b64 exec, s[10:11]
	v_cmp_le_u32_e32 vcc, 11, v28
	s_and_saveexec_b64 s[10:11], vcc
	global_load_dwordx4 v[104:107], v[162:163], off offset:-2048
	s_mov_b64 exec, s[10:11]
	v_cmp_le_u32_e32 vcc, 12, v28
	s_and_saveexec_b64 s[10:11], vcc
	global_load_dwordx4 v[108:111], v[162:163], off offset:-4096
	s_mov_b64 exec, s[10:11]
	v_cmp_le_u32_e32 vcc, 13, v28
	s_and_saveexec_b64 s[10:11], vcc
	global_load_dwordx4 v[112:115], v[160:161], off offset:2048
	s_mov_b64 exec, s[10:11]
	v_cmp_le_u32_e32 vcc, 14, v28
	s_and_saveexec_b64 s[10:11], vcc
	global_load_dwordx4 v[116:119], v[160:161], off
	s_mov_b64 exec, s[10:11]
	v_cmp_le_u32_e32 vcc, 15, v28
	s_and_saveexec_b64 s[10:11], vcc
	global_load_dwordx4 v[120:123], v[160:161], off offset:-2048
	s_mov_b64 exec, s[10:11]
	v_cmp_le_u32_e32 vcc, 16, v28
	s_and_saveexec_b64 s[10:11], vcc
	global_load_dwordx4 v[124:127], v[160:161], off offset:-4096
	s_mov_b64 exec, s[10:11]
	v_mov_b32_e32 v8, 0
	v_mov_b32_e32 v9, 0
	v_mov_b32_e32 v10, 0
	v_mov_b32_e32 v11, 0
	v_mov_b32_e32 v12, 0
	v_mov_b32_e32 v13, 0
	v_mov_b32_e32 v14, 0
	v_mov_b32_e32 v15, 0
	s_waitcnt vmcnt(0)
	v_lshlrev_b32_e32 v36, 16, v64
	v_and_b32_e32 v37, 0xffff0000, v64
	v_lshlrev_b32_e32 v38, 16, v65
	v_and_b32_e32 v39, 0xffff0000, v65
	v_lshlrev_b32_e32 v40, 16, v66
	v_and_b32_e32 v41, 0xffff0000, v66
	v_lshlrev_b32_e32 v42, 16, v67
	v_and_b32_e32 v43, 0xffff0000, v67
	v_pk_add_f32 v[8:9], v[8:9], v[36:37]
	v_pk_add_f32 v[10:11], v[10:11], v[38:39]
	v_pk_add_f32 v[12:13], v[12:13], v[40:41]
	v_pk_add_f32 v[14:15], v[14:15], v[42:43]
	v_lshlrev_b32_e32 v36, 16, v68
	v_and_b32_e32 v37, 0xffff0000, v68
	v_lshlrev_b32_e32 v38, 16, v69
	v_and_b32_e32 v39, 0xffff0000, v69
	v_lshlrev_b32_e32 v40, 16, v70
	v_and_b32_e32 v41, 0xffff0000, v70
	v_lshlrev_b32_e32 v42, 16, v71
	v_and_b32_e32 v43, 0xffff0000, v71
	v_pk_add_f32 v[8:9], v[8:9], v[36:37]
	v_pk_add_f32 v[10:11], v[10:11], v[38:39]
	v_pk_add_f32 v[12:13], v[12:13], v[40:41]
	v_pk_add_f32 v[14:15], v[14:15], v[42:43]
	v_lshlrev_b32_e32 v36, 16, v72
	v_and_b32_e32 v37, 0xffff0000, v72
	v_lshlrev_b32_e32 v38, 16, v73
	v_and_b32_e32 v39, 0xffff0000, v73
	v_lshlrev_b32_e32 v40, 16, v74
	v_and_b32_e32 v41, 0xffff0000, v74
	v_lshlrev_b32_e32 v42, 16, v75
	v_and_b32_e32 v43, 0xffff0000, v75
	v_pk_add_f32 v[8:9], v[8:9], v[36:37]
	v_pk_add_f32 v[10:11], v[10:11], v[38:39]
	v_pk_add_f32 v[12:13], v[12:13], v[40:41]
	v_pk_add_f32 v[14:15], v[14:15], v[42:43]
	v_lshlrev_b32_e32 v36, 16, v76
	v_and_b32_e32 v37, 0xffff0000, v76
	v_lshlrev_b32_e32 v38, 16, v77
	v_and_b32_e32 v39, 0xffff0000, v77
	v_lshlrev_b32_e32 v40, 16, v78
	v_and_b32_e32 v41, 0xffff0000, v78
	v_lshlrev_b32_e32 v42, 16, v79
	v_and_b32_e32 v43, 0xffff0000, v79
	v_pk_add_f32 v[8:9], v[8:9], v[36:37]
	v_pk_add_f32 v[10:11], v[10:11], v[38:39]
	v_pk_add_f32 v[12:13], v[12:13], v[40:41]
	v_pk_add_f32 v[14:15], v[14:15], v[42:43]
	v_lshlrev_b32_e32 v36, 16, v80
	v_and_b32_e32 v37, 0xffff0000, v80
	v_lshlrev_b32_e32 v38, 16, v81
	v_and_b32_e32 v39, 0xffff0000, v81
	v_lshlrev_b32_e32 v40, 16, v82
	v_and_b32_e32 v41, 0xffff0000, v82
	v_lshlrev_b32_e32 v42, 16, v83
	v_and_b32_e32 v43, 0xffff0000, v83
	v_pk_add_f32 v[8:9], v[8:9], v[36:37]
	v_pk_add_f32 v[10:11], v[10:11], v[38:39]
	v_pk_add_f32 v[12:13], v[12:13], v[40:41]
	v_pk_add_f32 v[14:15], v[14:15], v[42:43]
	v_lshlrev_b32_e32 v36, 16, v84
	v_and_b32_e32 v37, 0xffff0000, v84
	v_lshlrev_b32_e32 v38, 16, v85
	v_and_b32_e32 v39, 0xffff0000, v85
	v_lshlrev_b32_e32 v40, 16, v86
	v_and_b32_e32 v41, 0xffff0000, v86
	v_lshlrev_b32_e32 v42, 16, v87
	v_and_b32_e32 v43, 0xffff0000, v87
	v_pk_add_f32 v[8:9], v[8:9], v[36:37]
	v_pk_add_f32 v[10:11], v[10:11], v[38:39]
	v_pk_add_f32 v[12:13], v[12:13], v[40:41]
	v_pk_add_f32 v[14:15], v[14:15], v[42:43]
	v_lshlrev_b32_e32 v36, 16, v88
	v_and_b32_e32 v37, 0xffff0000, v88
	v_lshlrev_b32_e32 v38, 16, v89
	v_and_b32_e32 v39, 0xffff0000, v89
	v_lshlrev_b32_e32 v40, 16, v90
	v_and_b32_e32 v41, 0xffff0000, v90
	v_lshlrev_b32_e32 v42, 16, v91
	v_and_b32_e32 v43, 0xffff0000, v91
	v_pk_add_f32 v[8:9], v[8:9], v[36:37]
	v_pk_add_f32 v[10:11], v[10:11], v[38:39]
	v_pk_add_f32 v[12:13], v[12:13], v[40:41]
	v_pk_add_f32 v[14:15], v[14:15], v[42:43]
	v_lshlrev_b32_e32 v36, 16, v92
	v_and_b32_e32 v37, 0xffff0000, v92
	v_lshlrev_b32_e32 v38, 16, v93
	v_and_b32_e32 v39, 0xffff0000, v93
	v_lshlrev_b32_e32 v40, 16, v94
	v_and_b32_e32 v41, 0xffff0000, v94
	v_lshlrev_b32_e32 v42, 16, v95
	v_and_b32_e32 v43, 0xffff0000, v95
	v_pk_add_f32 v[8:9], v[8:9], v[36:37]
	v_pk_add_f32 v[10:11], v[10:11], v[38:39]
	v_pk_add_f32 v[12:13], v[12:13], v[40:41]
	v_pk_add_f32 v[14:15], v[14:15], v[42:43]
	v_lshlrev_b32_e32 v36, 16, v96
	v_and_b32_e32 v37, 0xffff0000, v96
	v_lshlrev_b32_e32 v38, 16, v97
	v_and_b32_e32 v39, 0xffff0000, v97
	v_lshlrev_b32_e32 v40, 16, v98
	v_and_b32_e32 v41, 0xffff0000, v98
	v_lshlrev_b32_e32 v42, 16, v99
	v_and_b32_e32 v43, 0xffff0000, v99
	v_pk_add_f32 v[8:9], v[8:9], v[36:37]
	v_pk_add_f32 v[10:11], v[10:11], v[38:39]
	v_pk_add_f32 v[12:13], v[12:13], v[40:41]
	v_pk_add_f32 v[14:15], v[14:15], v[42:43]
	v_lshlrev_b32_e32 v36, 16, v100
	v_and_b32_e32 v37, 0xffff0000, v100
	v_lshlrev_b32_e32 v38, 16, v101
	v_and_b32_e32 v39, 0xffff0000, v101
	v_lshlrev_b32_e32 v40, 16, v102
	v_and_b32_e32 v41, 0xffff0000, v102
	v_lshlrev_b32_e32 v42, 16, v103
	v_and_b32_e32 v43, 0xffff0000, v103
	v_pk_add_f32 v[8:9], v[8:9], v[36:37]
	v_pk_add_f32 v[10:11], v[10:11], v[38:39]
	v_pk_add_f32 v[12:13], v[12:13], v[40:41]
	v_pk_add_f32 v[14:15], v[14:15], v[42:43]
	v_lshlrev_b32_e32 v36, 16, v104
	v_and_b32_e32 v37, 0xffff0000, v104
	v_lshlrev_b32_e32 v38, 16, v105
	v_and_b32_e32 v39, 0xffff0000, v105
	v_lshlrev_b32_e32 v40, 16, v106
	v_and_b32_e32 v41, 0xffff0000, v106
	v_lshlrev_b32_e32 v42, 16, v107
	v_and_b32_e32 v43, 0xffff0000, v107
	v_pk_add_f32 v[8:9], v[8:9], v[36:37]
	v_pk_add_f32 v[10:11], v[10:11], v[38:39]
	v_pk_add_f32 v[12:13], v[12:13], v[40:41]
	v_pk_add_f32 v[14:15], v[14:15], v[42:43]
	v_lshlrev_b32_e32 v36, 16, v108
	v_and_b32_e32 v37, 0xffff0000, v108
	v_lshlrev_b32_e32 v38, 16, v109
	v_and_b32_e32 v39, 0xffff0000, v109
	v_lshlrev_b32_e32 v40, 16, v110
	v_and_b32_e32 v41, 0xffff0000, v110
	v_lshlrev_b32_e32 v42, 16, v111
	v_and_b32_e32 v43, 0xffff0000, v111
	v_pk_add_f32 v[8:9], v[8:9], v[36:37]
	v_pk_add_f32 v[10:11], v[10:11], v[38:39]
	v_pk_add_f32 v[12:13], v[12:13], v[40:41]
	v_pk_add_f32 v[14:15], v[14:15], v[42:43]
	v_lshlrev_b32_e32 v36, 16, v112
	v_and_b32_e32 v37, 0xffff0000, v112
	v_lshlrev_b32_e32 v38, 16, v113
	v_and_b32_e32 v39, 0xffff0000, v113
	v_lshlrev_b32_e32 v40, 16, v114
	v_and_b32_e32 v41, 0xffff0000, v114
	v_lshlrev_b32_e32 v42, 16, v115
	v_and_b32_e32 v43, 0xffff0000, v115
	v_pk_add_f32 v[8:9], v[8:9], v[36:37]
	v_pk_add_f32 v[10:11], v[10:11], v[38:39]
	v_pk_add_f32 v[12:13], v[12:13], v[40:41]
	v_pk_add_f32 v[14:15], v[14:15], v[42:43]
	v_lshlrev_b32_e32 v36, 16, v116
	v_and_b32_e32 v37, 0xffff0000, v116
	v_lshlrev_b32_e32 v38, 16, v117
	v_and_b32_e32 v39, 0xffff0000, v117
	v_lshlrev_b32_e32 v40, 16, v118
	v_and_b32_e32 v41, 0xffff0000, v118
	v_lshlrev_b32_e32 v42, 16, v119
	v_and_b32_e32 v43, 0xffff0000, v119
	v_pk_add_f32 v[8:9], v[8:9], v[36:37]
	v_pk_add_f32 v[10:11], v[10:11], v[38:39]
	v_pk_add_f32 v[12:13], v[12:13], v[40:41]
	v_pk_add_f32 v[14:15], v[14:15], v[42:43]
	v_lshlrev_b32_e32 v36, 16, v120
	v_and_b32_e32 v37, 0xffff0000, v120
	v_lshlrev_b32_e32 v38, 16, v121
	v_and_b32_e32 v39, 0xffff0000, v121
	v_lshlrev_b32_e32 v40, 16, v122
	v_and_b32_e32 v41, 0xffff0000, v122
	v_lshlrev_b32_e32 v42, 16, v123
	v_and_b32_e32 v43, 0xffff0000, v123
	v_pk_add_f32 v[8:9], v[8:9], v[36:37]
	v_pk_add_f32 v[10:11], v[10:11], v[38:39]
	v_pk_add_f32 v[12:13], v[12:13], v[40:41]
	v_pk_add_f32 v[14:15], v[14:15], v[42:43]
	v_lshlrev_b32_e32 v36, 16, v124
	v_and_b32_e32 v37, 0xffff0000, v124
	v_lshlrev_b32_e32 v38, 16, v125
	v_and_b32_e32 v39, 0xffff0000, v125
	v_lshlrev_b32_e32 v40, 16, v126
	v_and_b32_e32 v41, 0xffff0000, v126
	v_lshlrev_b32_e32 v42, 16, v127
	v_and_b32_e32 v43, 0xffff0000, v127
	v_pk_add_f32 v[8:9], v[8:9], v[36:37]
	v_pk_add_f32 v[10:11], v[10:11], v[38:39]
	v_pk_add_f32 v[12:13], v[12:13], v[40:41]
	v_pk_add_f32 v[14:15], v[14:15], v[42:43]
	v_lshlrev_b32_e32 v16, 16, v128
	v_and_b32_e32 v17, 0xffff0000, v128
	v_lshlrev_b32_e32 v18, 16, v129
	v_and_b32_e32 v19, 0xffff0000, v129
	v_lshlrev_b32_e32 v20, 16, v130
	v_and_b32_e32 v21, 0xffff0000, v130
	v_lshlrev_b32_e32 v22, 16, v131
	v_and_b32_e32 v23, 0xffff0000, v131
	v_pk_add_f32 v[8:9], v[8:9], v[16:17]
	v_pk_add_f32 v[10:11], v[10:11], v[18:19]
	v_pk_add_f32 v[12:13], v[12:13], v[20:21]
	v_pk_add_f32 v[14:15], v[14:15], v[22:23]
	v_cndmask_b32_e64 v44, v124, v92, s[8:9]
	v_cndmask_b32_e64 v44, v44, v76, s[6:7]
	v_cndmask_b32_e64 v44, v44, v68, s[4:5]
	v_cndmask_b32_e64 v45, v125, v93, s[8:9]
	v_cndmask_b32_e64 v45, v45, v77, s[6:7]
	v_cndmask_b32_e64 v45, v45, v69, s[4:5]
	v_cndmask_b32_e64 v46, v126, v94, s[8:9]
	v_cndmask_b32_e64 v46, v46, v78, s[6:7]
	v_cndmask_b32_e64 v46, v46, v70, s[4:5]
	v_cndmask_b32_e64 v47, v127, v95, s[8:9]
	v_cndmask_b32_e64 v47, v47, v79, s[6:7]
	v_cndmask_b32_e64 v47, v47, v71, s[4:5]
	v_lshlrev_b32_e32 v36, 16, v44
	v_and_b32_e32 v37, 0xffff0000, v44
	v_lshlrev_b32_e32 v38, 16, v45
	v_and_b32_e32 v39, 0xffff0000, v45
	v_lshlrev_b32_e32 v40, 16, v46
	v_and_b32_e32 v41, 0xffff0000, v46
	v_lshlrev_b32_e32 v42, 16, v47
	v_and_b32_e32 v43, 0xffff0000, v47
	v_pk_add_f32 v[8:9], v[8:9], v[36:37] neg_lo:[0,1] neg_hi:[0,1]
	v_pk_add_f32 v[10:11], v[10:11], v[38:39] neg_lo:[0,1] neg_hi:[0,1]
	v_pk_add_f32 v[12:13], v[12:13], v[40:41] neg_lo:[0,1] neg_hi:[0,1]
	v_pk_add_f32 v[14:15], v[14:15], v[42:43] neg_lo:[0,1] neg_hi:[0,1]
	v_add_u32_e32 v7, 1, v6
	v_min_i32_e32 v0, v7, v27
	v_cvt_f32_i32_e32 v0, v0
	v_div_scale_f32 v30, s[10:11], v0, v0, 1.0
	v_rcp_f32_e32 v31, v30
	v_div_scale_f32 v32, vcc, 1.0, v0, 1.0
	v_fma_f32 v33, -v30, v31, 1.0
	v_fmac_f32_e32 v31, v33, v31
	v_mul_f32_e32 v33, v32, v31
	v_fma_f32 v34, -v30, v33, v32
	v_fmac_f32_e32 v33, v34, v31
	v_fma_f32 v30, -v30, v33, v32
	v_div_fmas_f32 v30, v30, v31, v33
	v_div_fixup_f32 v0, v30, v0, 1.0
	v_pk_fma_f32 v[16:17], v[0:1], v[8:9], v[16:17] op_sel_hi:[0,1,1] neg_lo:[0,0,1] neg_hi:[0,0,1]
	v_pk_fma_f32 v[18:19], v[0:1], v[10:11], v[18:19] op_sel_hi:[0,1,1] neg_lo:[0,0,1] neg_hi:[0,0,1]
	v_pk_fma_f32 v[20:21], v[0:1], v[12:13], v[20:21] op_sel_hi:[0,1,1] neg_lo:[0,0,1] neg_hi:[0,0,1]
	v_pk_fma_f32 v[22:23], v[0:1], v[14:15], v[22:23] op_sel_hi:[0,1,1] neg_lo:[0,0,1] neg_hi:[0,0,1]
	v_cvt_pk_bf16_f32 v52, v16, v17
	v_cvt_pk_bf16_f32 v53, v18, v19
	v_cvt_pk_bf16_f32 v54, v20, v21
	v_cvt_pk_bf16_f32 v55, v22, v23
	global_store_dwordx4 v[172:173], v[52:55], off offset:-4096
	v_lshlrev_b32_e32 v16, 16, v132
	v_and_b32_e32 v17, 0xffff0000, v132
	v_lshlrev_b32_e32 v18, 16, v133
	v_and_b32_e32 v19, 0xffff0000, v133
	v_lshlrev_b32_e32 v20, 16, v134
	v_and_b32_e32 v21, 0xffff0000, v134
	v_lshlrev_b32_e32 v22, 16, v135
	v_and_b32_e32 v23, 0xffff0000, v135
	v_pk_add_f32 v[8:9], v[8:9], v[16:17]
	v_pk_add_f32 v[10:11], v[10:11], v[18:19]
	v_pk_add_f32 v[12:13], v[12:13], v[20:21]
	v_pk_add_f32 v[14:15], v[14:15], v[22:23]
	v_cndmask_b32_e64 v44, v120, v88, s[8:9]
	v_cndmask_b32_e64 v44, v44, v72, s[6:7]
	v_cndmask_b32_e64 v44, v44, v64, s[4:5]
	v_cndmask_b32_e64 v45, v121, v89, s[8:9]
	v_cndmask_b32_e64 v45, v45, v73, s[6:7]
	v_cndmask_b32_e64 v45, v45, v65, s[4:5]
	v_cndmask_b32_e64 v46, v122, v90, s[8:9]
	v_cndmask_b32_e64 v46, v46, v74, s[6:7]
	v_cndmask_b32_e64 v46, v46, v66, s[4:5]
	v_cndmask_b32_e64 v47, v123, v91, s[8:9]
	v_cndmask_b32_e64 v47, v47, v75, s[6:7]
	v_cndmask_b32_e64 v47, v47, v67, s[4:5]
	v_lshlrev_b32_e32 v36, 16, v44
	v_and_b32_e32 v37, 0xffff0000, v44
	v_lshlrev_b32_e32 v38, 16, v45
	v_and_b32_e32 v39, 0xffff0000, v45
	v_lshlrev_b32_e32 v40, 16, v46
	v_and_b32_e32 v41, 0xffff0000, v46
	v_lshlrev_b32_e32 v42, 16, v47
	v_and_b32_e32 v43, 0xffff0000, v47
	v_pk_add_f32 v[8:9], v[8:9], v[36:37] neg_lo:[0,1] neg_hi:[0,1]
	v_pk_add_f32 v[10:11], v[10:11], v[38:39] neg_lo:[0,1] neg_hi:[0,1]
	v_pk_add_f32 v[12:13], v[12:13], v[40:41] neg_lo:[0,1] neg_hi:[0,1]
	v_pk_add_f32 v[14:15], v[14:15], v[42:43] neg_lo:[0,1] neg_hi:[0,1]
	v_add_u32_e32 v7, 2, v6
	v_min_i32_e32 v0, v7, v27
	v_cvt_f32_i32_e32 v0, v0
	v_div_scale_f32 v30, s[10:11], v0, v0, 1.0
	v_rcp_f32_e32 v31, v30
	v_div_scale_f32 v32, vcc, 1.0, v0, 1.0
	v_fma_f32 v33, -v30, v31, 1.0
	v_fmac_f32_e32 v31, v33, v31
	v_mul_f32_e32 v33, v32, v31
	v_fma_f32 v34, -v30, v33, v32
	v_fmac_f32_e32 v33, v34, v31
	v_fma_f32 v30, -v30, v33, v32
	v_div_fmas_f32 v30, v30, v31, v33
	v_div_fixup_f32 v0, v30, v0, 1.0
	v_pk_fma_f32 v[16:17], v[0:1], v[8:9], v[16:17] op_sel_hi:[0,1,1] neg_lo:[0,0,1] neg_hi:[0,0,1]
	v_pk_fma_f32 v[18:19], v[0:1], v[10:11], v[18:19] op_sel_hi:[0,1,1] neg_lo:[0,0,1] neg_hi:[0,0,1]
	v_pk_fma_f32 v[20:21], v[0:1], v[12:13], v[20:21] op_sel_hi:[0,1,1] neg_lo:[0,0,1] neg_hi:[0,0,1]
	v_pk_fma_f32 v[22:23], v[0:1], v[14:15], v[22:23] op_sel_hi:[0,1,1] neg_lo:[0,0,1] neg_hi:[0,0,1]
	v_cvt_pk_bf16_f32 v56, v16, v17
	v_cvt_pk_bf16_f32 v57, v18, v19
	v_cvt_pk_bf16_f32 v58, v20, v21
	v_cvt_pk_bf16_f32 v59, v22, v23
	global_store_dwordx4 v[172:173], v[56:59], off offset:-2048
	v_lshlrev_b32_e32 v16, 16, v136
	v_and_b32_e32 v17, 0xffff0000, v136
	v_lshlrev_b32_e32 v18, 16, v137
	v_and_b32_e32 v19, 0xffff0000, v137
	v_lshlrev_b32_e32 v20, 16, v138
	v_and_b32_e32 v21, 0xffff0000, v138
	v_lshlrev_b32_e32 v22, 16, v139
	v_and_b32_e32 v23, 0xffff0000, v139
	v_pk_add_f32 v[8:9], v[8:9], v[16:17]
	v_pk_add_f32 v[10:11], v[10:11], v[18:19]
	v_pk_add_f32 v[12:13], v[12:13], v[20:21]
	v_pk_add_f32 v[14:15], v[14:15], v[22:23]
	v_cndmask_b32_e64 v44, v116, v84, s[8:9]
	v_cndmask_b32_e64 v44, v44, v68, s[6:7]
	v_cndmask_b32_e64 v44, v44, v128, s[4:5]
	v_cndmask_b32_e64 v45, v117, v85, s[8:9]
	v_cndmask_b32_e64 v45, v45, v69, s[6:7]
	v_cndmask_b32_e64 v45, v45, v129, s[4:5]
	v_cndmask_b32_e64 v46, v118, v86, s[8:9]
	v_cndmask_b32_e64 v46, v46, v70, s[6:7]
	v_cndmask_b32_e64 v46, v46, v130, s[4:5]
	v_cndmask_b32_e64 v47, v119, v87, s[8:9]
	v_cndmask_b32_e64 v47, v47, v71, s[6:7]
	v_cndmask_b32_e64 v47, v47, v131, s[4:5]
	v_lshlrev_b32_e32 v36, 16, v44
	v_and_b32_e32 v37, 0xffff0000, v44
	v_lshlrev_b32_e32 v38, 16, v45
	v_and_b32_e32 v39, 0xffff0000, v45
	v_lshlrev_b32_e32 v40, 16, v46
	v_and_b32_e32 v41, 0xffff0000, v46
	v_lshlrev_b32_e32 v42, 16, v47
	v_and_b32_e32 v43, 0xffff0000, v47
	v_pk_add_f32 v[8:9], v[8:9], v[36:37] neg_lo:[0,1] neg_hi:[0,1]
	v_pk_add_f32 v[10:11], v[10:11], v[38:39] neg_lo:[0,1] neg_hi:[0,1]
	v_pk_add_f32 v[12:13], v[12:13], v[40:41] neg_lo:[0,1] neg_hi:[0,1]
	v_pk_add_f32 v[14:15], v[14:15], v[42:43] neg_lo:[0,1] neg_hi:[0,1]
	v_add_u32_e32 v7, 3, v6
	v_min_i32_e32 v0, v7, v27
	v_cvt_f32_i32_e32 v0, v0
	v_div_scale_f32 v30, s[10:11], v0, v0, 1.0
	v_rcp_f32_e32 v31, v30
	v_div_scale_f32 v32, vcc, 1.0, v0, 1.0
	v_fma_f32 v33, -v30, v31, 1.0
	v_fmac_f32_e32 v31, v33, v31
	v_mul_f32_e32 v33, v32, v31
	v_fma_f32 v34, -v30, v33, v32
	v_fmac_f32_e32 v33, v34, v31
	v_fma_f32 v30, -v30, v33, v32
	v_div_fmas_f32 v30, v30, v31, v33
	v_div_fixup_f32 v0, v30, v0, 1.0
	v_pk_fma_f32 v[16:17], v[0:1], v[8:9], v[16:17] op_sel_hi:[0,1,1] neg_lo:[0,0,1] neg_hi:[0,0,1]
	v_pk_fma_f32 v[18:19], v[0:1], v[10:11], v[18:19] op_sel_hi:[0,1,1] neg_lo:[0,0,1] neg_hi:[0,0,1]
	v_pk_fma_f32 v[20:21], v[0:1], v[12:13], v[20:21] op_sel_hi:[0,1,1] neg_lo:[0,0,1] neg_hi:[0,0,1]
	v_pk_fma_f32 v[22:23], v[0:1], v[14:15], v[22:23] op_sel_hi:[0,1,1] neg_lo:[0,0,1] neg_hi:[0,0,1]
	v_cvt_pk_bf16_f32 v52, v16, v17
	v_cvt_pk_bf16_f32 v53, v18, v19
	v_cvt_pk_bf16_f32 v54, v20, v21
	v_cvt_pk_bf16_f32 v55, v22, v23
	global_store_dwordx4 v[172:173], v[52:55], off
	v_lshlrev_b32_e32 v16, 16, v140
	v_and_b32_e32 v17, 0xffff0000, v140
	v_lshlrev_b32_e32 v18, 16, v141
	v_and_b32_e32 v19, 0xffff0000, v141
	v_lshlrev_b32_e32 v20, 16, v142
	v_and_b32_e32 v21, 0xffff0000, v142
	v_lshlrev_b32_e32 v22, 16, v143
	v_and_b32_e32 v23, 0xffff0000, v143
	v_pk_add_f32 v[8:9], v[8:9], v[16:17]
	v_pk_add_f32 v[10:11], v[10:11], v[18:19]
	v_pk_add_f32 v[12:13], v[12:13], v[20:21]
	v_pk_add_f32 v[14:15], v[14:15], v[22:23]
	v_cndmask_b32_e64 v44, v112, v80, s[8:9]
	v_cndmask_b32_e64 v44, v44, v64, s[6:7]
	v_cndmask_b32_e64 v44, v44, v132, s[4:5]
	v_cndmask_b32_e64 v45, v113, v81, s[8:9]
	v_cndmask_b32_e64 v45, v45, v65, s[6:7]
	v_cndmask_b32_e64 v45, v45, v133, s[4:5]
	v_cndmask_b32_e64 v46, v114, v82, s[8:9]
	v_cndmask_b32_e64 v46, v46, v66, s[6:7]
	v_cndmask_b32_e64 v46, v46, v134, s[4:5]
	v_cndmask_b32_e64 v47, v115, v83, s[8:9]
	v_cndmask_b32_e64 v47, v47, v67, s[6:7]
	v_cndmask_b32_e64 v47, v47, v135, s[4:5]
	v_lshlrev_b32_e32 v36, 16, v44
	v_and_b32_e32 v37, 0xffff0000, v44
	v_lshlrev_b32_e32 v38, 16, v45
	v_and_b32_e32 v39, 0xffff0000, v45
	v_lshlrev_b32_e32 v40, 16, v46
	v_and_b32_e32 v41, 0xffff0000, v46
	v_lshlrev_b32_e32 v42, 16, v47
	v_and_b32_e32 v43, 0xffff0000, v47
	v_pk_add_f32 v[8:9], v[8:9], v[36:37] neg_lo:[0,1] neg_hi:[0,1]
	v_pk_add_f32 v[10:11], v[10:11], v[38:39] neg_lo:[0,1] neg_hi:[0,1]
	v_pk_add_f32 v[12:13], v[12:13], v[40:41] neg_lo:[0,1] neg_hi:[0,1]
	v_pk_add_f32 v[14:15], v[14:15], v[42:43] neg_lo:[0,1] neg_hi:[0,1]
	v_add_u32_e32 v7, 4, v6
	v_min_i32_e32 v0, v7, v27
	v_cvt_f32_i32_e32 v0, v0
	v_div_scale_f32 v30, s[10:11], v0, v0, 1.0
	v_rcp_f32_e32 v31, v30
	v_div_scale_f32 v32, vcc, 1.0, v0, 1.0
	v_fma_f32 v33, -v30, v31, 1.0
	v_fmac_f32_e32 v31, v33, v31
	v_mul_f32_e32 v33, v32, v31
	v_fma_f32 v34, -v30, v33, v32
	v_fmac_f32_e32 v33, v34, v31
	v_fma_f32 v30, -v30, v33, v32
	v_div_fmas_f32 v30, v30, v31, v33
	v_div_fixup_f32 v0, v30, v0, 1.0
	v_pk_fma_f32 v[16:17], v[0:1], v[8:9], v[16:17] op_sel_hi:[0,1,1] neg_lo:[0,0,1] neg_hi:[0,0,1]
	v_pk_fma_f32 v[18:19], v[0:1], v[10:11], v[18:19] op_sel_hi:[0,1,1] neg_lo:[0,0,1] neg_hi:[0,0,1]
	v_pk_fma_f32 v[20:21], v[0:1], v[12:13], v[20:21] op_sel_hi:[0,1,1] neg_lo:[0,0,1] neg_hi:[0,0,1]
	v_pk_fma_f32 v[22:23], v[0:1], v[14:15], v[22:23] op_sel_hi:[0,1,1] neg_lo:[0,0,1] neg_hi:[0,0,1]
	v_cvt_pk_bf16_f32 v56, v16, v17
	v_cvt_pk_bf16_f32 v57, v18, v19
	v_cvt_pk_bf16_f32 v58, v20, v21
	v_cvt_pk_bf16_f32 v59, v22, v23
	global_store_dwordx4 v[172:173], v[56:59], off offset:2048
	v_lshlrev_b32_e32 v16, 16, v144
	v_and_b32_e32 v17, 0xffff0000, v144
	v_lshlrev_b32_e32 v18, 16, v145
	v_and_b32_e32 v19, 0xffff0000, v145
	v_lshlrev_b32_e32 v20, 16, v146
	v_and_b32_e32 v21, 0xffff0000, v146
	v_lshlrev_b32_e32 v22, 16, v147
	v_and_b32_e32 v23, 0xffff0000, v147
	v_pk_add_f32 v[8:9], v[8:9], v[16:17]
	v_pk_add_f32 v[10:11], v[10:11], v[18:19]
	v_pk_add_f32 v[12:13], v[12:13], v[20:21]
	v_pk_add_f32 v[14:15], v[14:15], v[22:23]
	v_cndmask_b32_e64 v44, v108, v76, s[8:9]
	v_cndmask_b32_e64 v44, v44, v128, s[6:7]
	v_cndmask_b32_e64 v44, v44, v136, s[4:5]
	v_cndmask_b32_e64 v45, v109, v77, s[8:9]
	v_cndmask_b32_e64 v45, v45, v129, s[6:7]
	v_cndmask_b32_e64 v45, v45, v137, s[4:5]
	v_cndmask_b32_e64 v46, v110, v78, s[8:9]
	v_cndmask_b32_e64 v46, v46, v130, s[6:7]
	v_cndmask_b32_e64 v46, v46, v138, s[4:5]
	v_cndmask_b32_e64 v47, v111, v79, s[8:9]
	v_cndmask_b32_e64 v47, v47, v131, s[6:7]
	v_cndmask_b32_e64 v47, v47, v139, s[4:5]
	v_lshlrev_b32_e32 v36, 16, v44
	v_and_b32_e32 v37, 0xffff0000, v44
	v_lshlrev_b32_e32 v38, 16, v45
	v_and_b32_e32 v39, 0xffff0000, v45
	v_lshlrev_b32_e32 v40, 16, v46
	v_and_b32_e32 v41, 0xffff0000, v46
	v_lshlrev_b32_e32 v42, 16, v47
	v_and_b32_e32 v43, 0xffff0000, v47
	v_pk_add_f32 v[8:9], v[8:9], v[36:37] neg_lo:[0,1] neg_hi:[0,1]
	v_pk_add_f32 v[10:11], v[10:11], v[38:39] neg_lo:[0,1] neg_hi:[0,1]
	v_pk_add_f32 v[12:13], v[12:13], v[40:41] neg_lo:[0,1] neg_hi:[0,1]
	v_pk_add_f32 v[14:15], v[14:15], v[42:43] neg_lo:[0,1] neg_hi:[0,1]
	v_add_u32_e32 v7, 5, v6
	v_min_i32_e32 v0, v7, v27
	v_cvt_f32_i32_e32 v0, v0
	v_div_scale_f32 v30, s[10:11], v0, v0, 1.0
	v_rcp_f32_e32 v31, v30
	v_div_scale_f32 v32, vcc, 1.0, v0, 1.0
	v_fma_f32 v33, -v30, v31, 1.0
	v_fmac_f32_e32 v31, v33, v31
	v_mul_f32_e32 v33, v32, v31
	v_fma_f32 v34, -v30, v33, v32
	v_fmac_f32_e32 v33, v34, v31
	v_fma_f32 v30, -v30, v33, v32
	v_div_fmas_f32 v30, v30, v31, v33
	v_div_fixup_f32 v0, v30, v0, 1.0
	v_pk_fma_f32 v[16:17], v[0:1], v[8:9], v[16:17] op_sel_hi:[0,1,1] neg_lo:[0,0,1] neg_hi:[0,0,1]
	v_pk_fma_f32 v[18:19], v[0:1], v[10:11], v[18:19] op_sel_hi:[0,1,1] neg_lo:[0,0,1] neg_hi:[0,0,1]
	v_pk_fma_f32 v[20:21], v[0:1], v[12:13], v[20:21] op_sel_hi:[0,1,1] neg_lo:[0,0,1] neg_hi:[0,0,1]
	v_pk_fma_f32 v[22:23], v[0:1], v[14:15], v[22:23] op_sel_hi:[0,1,1] neg_lo:[0,0,1] neg_hi:[0,0,1]
	v_cvt_pk_bf16_f32 v52, v16, v17
	v_cvt_pk_bf16_f32 v53, v18, v19
	v_cvt_pk_bf16_f32 v54, v20, v21
	v_cvt_pk_bf16_f32 v55, v22, v23
	global_store_dwordx4 v[174:175], v[52:55], off offset:-4096
	v_lshlrev_b32_e32 v16, 16, v148
	v_and_b32_e32 v17, 0xffff0000, v148
	v_lshlrev_b32_e32 v18, 16, v149
	v_and_b32_e32 v19, 0xffff0000, v149
	v_lshlrev_b32_e32 v20, 16, v150
	v_and_b32_e32 v21, 0xffff0000, v150
	v_lshlrev_b32_e32 v22, 16, v151
	v_and_b32_e32 v23, 0xffff0000, v151
	v_pk_add_f32 v[8:9], v[8:9], v[16:17]
	v_pk_add_f32 v[10:11], v[10:11], v[18:19]
	v_pk_add_f32 v[12:13], v[12:13], v[20:21]
	v_pk_add_f32 v[14:15], v[14:15], v[22:23]
	v_cndmask_b32_e64 v44, v104, v72, s[8:9]
	v_cndmask_b32_e64 v44, v44, v132, s[6:7]
	v_cndmask_b32_e64 v44, v44, v140, s[4:5]
	v_cndmask_b32_e64 v45, v105, v73, s[8:9]
	v_cndmask_b32_e64 v45, v45, v133, s[6:7]
	v_cndmask_b32_e64 v45, v45, v141, s[4:5]
	v_cndmask_b32_e64 v46, v106, v74, s[8:9]
	v_cndmask_b32_e64 v46, v46, v134, s[6:7]
	v_cndmask_b32_e64 v46, v46, v142, s[4:5]
	v_cndmask_b32_e64 v47, v107, v75, s[8:9]
	v_cndmask_b32_e64 v47, v47, v135, s[6:7]
	v_cndmask_b32_e64 v47, v47, v143, s[4:5]
	v_lshlrev_b32_e32 v36, 16, v44
	v_and_b32_e32 v37, 0xffff0000, v44
	v_lshlrev_b32_e32 v38, 16, v45
	v_and_b32_e32 v39, 0xffff0000, v45
	v_lshlrev_b32_e32 v40, 16, v46
	v_and_b32_e32 v41, 0xffff0000, v46
	v_lshlrev_b32_e32 v42, 16, v47
	v_and_b32_e32 v43, 0xffff0000, v47
	v_pk_add_f32 v[8:9], v[8:9], v[36:37] neg_lo:[0,1] neg_hi:[0,1]
	v_pk_add_f32 v[10:11], v[10:11], v[38:39] neg_lo:[0,1] neg_hi:[0,1]
	v_pk_add_f32 v[12:13], v[12:13], v[40:41] neg_lo:[0,1] neg_hi:[0,1]
	v_pk_add_f32 v[14:15], v[14:15], v[42:43] neg_lo:[0,1] neg_hi:[0,1]
	v_add_u32_e32 v7, 6, v6
	v_min_i32_e32 v0, v7, v27
	v_cvt_f32_i32_e32 v0, v0
	v_div_scale_f32 v30, s[10:11], v0, v0, 1.0
	v_rcp_f32_e32 v31, v30
	v_div_scale_f32 v32, vcc, 1.0, v0, 1.0
	v_fma_f32 v33, -v30, v31, 1.0
	v_fmac_f32_e32 v31, v33, v31
	v_mul_f32_e32 v33, v32, v31
	v_fma_f32 v34, -v30, v33, v32
	v_fmac_f32_e32 v33, v34, v31
	v_fma_f32 v30, -v30, v33, v32
	v_div_fmas_f32 v30, v30, v31, v33
	v_div_fixup_f32 v0, v30, v0, 1.0
	v_pk_fma_f32 v[16:17], v[0:1], v[8:9], v[16:17] op_sel_hi:[0,1,1] neg_lo:[0,0,1] neg_hi:[0,0,1]
	v_pk_fma_f32 v[18:19], v[0:1], v[10:11], v[18:19] op_sel_hi:[0,1,1] neg_lo:[0,0,1] neg_hi:[0,0,1]
	v_pk_fma_f32 v[20:21], v[0:1], v[12:13], v[20:21] op_sel_hi:[0,1,1] neg_lo:[0,0,1] neg_hi:[0,0,1]
	v_pk_fma_f32 v[22:23], v[0:1], v[14:15], v[22:23] op_sel_hi:[0,1,1] neg_lo:[0,0,1] neg_hi:[0,0,1]
	v_cvt_pk_bf16_f32 v56, v16, v17
	v_cvt_pk_bf16_f32 v57, v18, v19
	v_cvt_pk_bf16_f32 v58, v20, v21
	v_cvt_pk_bf16_f32 v59, v22, v23
	global_store_dwordx4 v[174:175], v[56:59], off offset:-2048
	v_lshlrev_b32_e32 v16, 16, v152
	v_and_b32_e32 v17, 0xffff0000, v152
	v_lshlrev_b32_e32 v18, 16, v153
	v_and_b32_e32 v19, 0xffff0000, v153
	v_lshlrev_b32_e32 v20, 16, v154
	v_and_b32_e32 v21, 0xffff0000, v154
	v_lshlrev_b32_e32 v22, 16, v155
	v_and_b32_e32 v23, 0xffff0000, v155
	v_pk_add_f32 v[8:9], v[8:9], v[16:17]
	v_pk_add_f32 v[10:11], v[10:11], v[18:19]
	v_pk_add_f32 v[12:13], v[12:13], v[20:21]
	v_pk_add_f32 v[14:15], v[14:15], v[22:23]
	v_cndmask_b32_e64 v44, v100, v68, s[8:9]
	v_cndmask_b32_e64 v44, v44, v136, s[6:7]
	v_cndmask_b32_e64 v44, v44, v144, s[4:5]
	v_cndmask_b32_e64 v45, v101, v69, s[8:9]
	v_cndmask_b32_e64 v45, v45, v137, s[6:7]
	v_cndmask_b32_e64 v45, v45, v145, s[4:5]
	v_cndmask_b32_e64 v46, v102, v70, s[8:9]
	v_cndmask_b32_e64 v46, v46, v138, s[6:7]
	v_cndmask_b32_e64 v46, v46, v146, s[4:5]
	v_cndmask_b32_e64 v47, v103, v71, s[8:9]
	v_cndmask_b32_e64 v47, v47, v139, s[6:7]
	v_cndmask_b32_e64 v47, v47, v147, s[4:5]
	v_lshlrev_b32_e32 v36, 16, v44
	v_and_b32_e32 v37, 0xffff0000, v44
	v_lshlrev_b32_e32 v38, 16, v45
	v_and_b32_e32 v39, 0xffff0000, v45
	v_lshlrev_b32_e32 v40, 16, v46
	v_and_b32_e32 v41, 0xffff0000, v46
	v_lshlrev_b32_e32 v42, 16, v47
	v_and_b32_e32 v43, 0xffff0000, v47
	v_pk_add_f32 v[8:9], v[8:9], v[36:37] neg_lo:[0,1] neg_hi:[0,1]
	v_pk_add_f32 v[10:11], v[10:11], v[38:39] neg_lo:[0,1] neg_hi:[0,1]
	v_pk_add_f32 v[12:13], v[12:13], v[40:41] neg_lo:[0,1] neg_hi:[0,1]
	v_pk_add_f32 v[14:15], v[14:15], v[42:43] neg_lo:[0,1] neg_hi:[0,1]
	v_add_u32_e32 v7, 7, v6
	v_min_i32_e32 v0, v7, v27
	v_cvt_f32_i32_e32 v0, v0
	v_div_scale_f32 v30, s[10:11], v0, v0, 1.0
	v_rcp_f32_e32 v31, v30
	v_div_scale_f32 v32, vcc, 1.0, v0, 1.0
	v_fma_f32 v33, -v30, v31, 1.0
	v_fmac_f32_e32 v31, v33, v31
	v_mul_f32_e32 v33, v32, v31
	v_fma_f32 v34, -v30, v33, v32
	v_fmac_f32_e32 v33, v34, v31
	v_fma_f32 v30, -v30, v33, v32
	v_div_fmas_f32 v30, v30, v31, v33
	v_div_fixup_f32 v0, v30, v0, 1.0
	v_pk_fma_f32 v[16:17], v[0:1], v[8:9], v[16:17] op_sel_hi:[0,1,1] neg_lo:[0,0,1] neg_hi:[0,0,1]
	v_pk_fma_f32 v[18:19], v[0:1], v[10:11], v[18:19] op_sel_hi:[0,1,1] neg_lo:[0,0,1] neg_hi:[0,0,1]
	v_pk_fma_f32 v[20:21], v[0:1], v[12:13], v[20:21] op_sel_hi:[0,1,1] neg_lo:[0,0,1] neg_hi:[0,0,1]
	v_pk_fma_f32 v[22:23], v[0:1], v[14:15], v[22:23] op_sel_hi:[0,1,1] neg_lo:[0,0,1] neg_hi:[0,0,1]
	v_cvt_pk_bf16_f32 v52, v16, v17
	v_cvt_pk_bf16_f32 v53, v18, v19
	v_cvt_pk_bf16_f32 v54, v20, v21
	v_cvt_pk_bf16_f32 v55, v22, v23
	global_store_dwordx4 v[174:175], v[52:55], off
	v_lshlrev_b32_e32 v16, 16, v156
	v_and_b32_e32 v17, 0xffff0000, v156
	v_lshlrev_b32_e32 v18, 16, v157
	v_and_b32_e32 v19, 0xffff0000, v157
	v_lshlrev_b32_e32 v20, 16, v158
	v_and_b32_e32 v21, 0xffff0000, v158
	v_lshlrev_b32_e32 v22, 16, v159
	v_and_b32_e32 v23, 0xffff0000, v159
	v_pk_add_f32 v[8:9], v[8:9], v[16:17]
	v_pk_add_f32 v[10:11], v[10:11], v[18:19]
	v_pk_add_f32 v[12:13], v[12:13], v[20:21]
	v_pk_add_f32 v[14:15], v[14:15], v[22:23]
	v_cndmask_b32_e64 v44, v96, v64, s[8:9]
	v_cndmask_b32_e64 v44, v44, v140, s[6:7]
	v_cndmask_b32_e64 v44, v44, v148, s[4:5]
	v_cndmask_b32_e64 v45, v97, v65, s[8:9]
	v_cndmask_b32_e64 v45, v45, v141, s[6:7]
	v_cndmask_b32_e64 v45, v45, v149, s[4:5]
	v_cndmask_b32_e64 v46, v98, v66, s[8:9]
	v_cndmask_b32_e64 v46, v46, v142, s[6:7]
	v_cndmask_b32_e64 v46, v46, v150, s[4:5]
	v_cndmask_b32_e64 v47, v99, v67, s[8:9]
	v_cndmask_b32_e64 v47, v47, v143, s[6:7]
	v_cndmask_b32_e64 v47, v47, v151, s[4:5]
	v_lshlrev_b32_e32 v36, 16, v44
	v_and_b32_e32 v37, 0xffff0000, v44
	v_lshlrev_b32_e32 v38, 16, v45
	v_and_b32_e32 v39, 0xffff0000, v45
	v_lshlrev_b32_e32 v40, 16, v46
	v_and_b32_e32 v41, 0xffff0000, v46
	v_lshlrev_b32_e32 v42, 16, v47
	v_and_b32_e32 v43, 0xffff0000, v47
	v_pk_add_f32 v[8:9], v[8:9], v[36:37] neg_lo:[0,1] neg_hi:[0,1]
	v_pk_add_f32 v[10:11], v[10:11], v[38:39] neg_lo:[0,1] neg_hi:[0,1]
	v_pk_add_f32 v[12:13], v[12:13], v[40:41] neg_lo:[0,1] neg_hi:[0,1]
	v_pk_add_f32 v[14:15], v[14:15], v[42:43] neg_lo:[0,1] neg_hi:[0,1]
	v_add_u32_e32 v7, 8, v6
	v_min_i32_e32 v0, v7, v27
	v_cvt_f32_i32_e32 v0, v0
	v_div_scale_f32 v30, s[10:11], v0, v0, 1.0
	v_rcp_f32_e32 v31, v30
	v_div_scale_f32 v32, vcc, 1.0, v0, 1.0
	v_fma_f32 v33, -v30, v31, 1.0
	v_fmac_f32_e32 v31, v33, v31
	v_mul_f32_e32 v33, v32, v31
	v_fma_f32 v34, -v30, v33, v32
	v_fmac_f32_e32 v33, v34, v31
	v_fma_f32 v30, -v30, v33, v32
	v_div_fmas_f32 v30, v30, v31, v33
	v_div_fixup_f32 v0, v30, v0, 1.0
	v_pk_fma_f32 v[16:17], v[0:1], v[8:9], v[16:17] op_sel_hi:[0,1,1] neg_lo:[0,0,1] neg_hi:[0,0,1]
	v_pk_fma_f32 v[18:19], v[0:1], v[10:11], v[18:19] op_sel_hi:[0,1,1] neg_lo:[0,0,1] neg_hi:[0,0,1]
	v_pk_fma_f32 v[20:21], v[0:1], v[12:13], v[20:21] op_sel_hi:[0,1,1] neg_lo:[0,0,1] neg_hi:[0,0,1]
	v_pk_fma_f32 v[22:23], v[0:1], v[14:15], v[22:23] op_sel_hi:[0,1,1] neg_lo:[0,0,1] neg_hi:[0,0,1]
	v_cvt_pk_bf16_f32 v56, v16, v17
	v_cvt_pk_bf16_f32 v57, v18, v19
	v_cvt_pk_bf16_f32 v58, v20, v21
	v_cvt_pk_bf16_f32 v59, v22, v23
	global_store_dwordx4 v[174:175], v[56:59], off offset:2048
	v_add_u32_e32 v26, s1, v26
	v_cmp_lt_i32_e32 vcc, s12, v26
	s_or_b64 s[14:15], vcc, s[14:15]
	s_andn2_b64 exec, exec, s[14:15]
	s_cbranch_execnz .Lpl_item
.LBB0_736:
	s_or_b64 exec, exec, s[2:3]
	s_cmpk_gt_i32 s0, 0x2bff
	s_cbranch_scc1 .LBB0_741
	v_mbcnt_hi_u32_b32 v0, -1, v193
	v_and_b32_e32 v1, 64, v0
	v_add_u32_e32 v1, 64, v1
	v_xor_b32_e32 v2, 1, v0
	v_cmp_lt_i32_e32 vcc, v2, v1
	s_add_u32 s2, s78, 0x206000
	s_addc_u32 s3, s79, 0
	v_cndmask_b32_e32 v2, v0, v2, vcc
	v_lshlrev_b32_e32 v12, 2, v2
	v_xor_b32_e32 v2, 2, v0
	v_cmp_lt_i32_e32 vcc, v2, v1
	s_ashr_i32 s1, s0, 31
	v_cmp_eq_u32_e64 s[4:5], 0, v50
	v_cndmask_b32_e32 v2, v0, v2, vcc
	v_lshlrev_b32_e32 v13, 2, v2
	v_xor_b32_e32 v2, 4, v0
	v_cmp_lt_i32_e32 vcc, v2, v1
	s_nop 1
	v_cndmask_b32_e32 v2, v0, v2, vcc
	v_lshlrev_b32_e32 v14, 2, v2
	v_xor_b32_e32 v2, 8, v0
	v_cmp_lt_i32_e32 vcc, v2, v1
	s_nop 1
	v_cndmask_b32_e32 v2, v0, v2, vcc
	v_lshlrev_b32_e32 v15, 2, v2
	v_xor_b32_e32 v2, 16, v0
	v_cmp_lt_i32_e32 vcc, v2, v1
	s_nop 1
	v_cndmask_b32_e32 v2, v0, v2, vcc
	v_lshlrev_b32_e32 v16, 2, v2
	v_xor_b32_e32 v2, 32, v0
	v_cmp_lt_i32_e32 vcc, v2, v1
	v_mov_b32_e32 v1, 0
	v_mov_b32_e32 v5, v1
	v_cndmask_b32_e32 v0, v0, v2, vcc
	v_lshlrev_b32_e32 v17, 2, v0
	v_lshlrev_b32_e32 v0, 5, v50
	v_lshl_add_u64 v[2:3], s[2:3], 0, v[0:1]
	v_or_b32_e32 v4, 0x800, v0
	v_or_b32_e32 v6, 0x1000, v0
	v_mov_b32_e32 v7, v1
	v_or_b32_e32 v0, 0x1800, v0
	v_lshl_add_u64 v[4:5], s[2:3], 0, v[4:5]
	v_lshl_add_u64 v[6:7], s[2:3], 0, v[6:7]
	v_lshl_add_u64 v[8:9], s[2:3], 0, v[0:1]
	s_lshl_b64 s[2:3], s[0:1], 2
	s_add_u32 s10, s2, 0x210000
	s_addc_u32 s11, s3, 0
	v_readlane_b32 s2, v254, 36
	s_mov_b32 s8, s2
	s_lshl_b64 s[6:7], s[0:1], 12
	v_lshl_or_b32 v10, v50, 4, s6
	s_mov_b32 s6, s8
	v_readlane_b32 s3, v254, 37
	s_ashr_i32 s9, s2, 31
	v_mov_b32_e32 v11, s7
	v_writelane_b32 v254, s6, 36
	s_lshl_b64 s[2:3], s[8:9], 2
	s_nop 0
	v_writelane_b32 v254, s7, 37
	s_lshl_b64 s[6:7], s[8:9], 12
	global_load_dwordx4 v[96:99], v[2:3], off
	global_load_dwordx4 v[100:103], v[2:3], off offset:16
	global_load_dwordx4 v[104:107], v[4:5], off
	global_load_dwordx4 v[108:111], v[4:5], off offset:16
	global_load_dwordx4 v[112:115], v[6:7], off
	global_load_dwordx4 v[116:119], v[6:7], off offset:16
	global_load_dwordx4 v[120:123], v[8:9], off
	global_load_dwordx4 v[124:127], v[8:9], off offset:16
.Lbu_outer:
	v_lshl_add_u64 v[18:19], s[78:79], 0, v[10:11]
	v_add_co_u32_e32 v18, vcc, 0x7000000, v18
	s_mov_b32 s12, s0
	s_nop 0
	v_addc_co_u32_e32 v19, vcc, 0, v19, vcc
	global_load_dwordx4 v[128:131], v[18:19], off
	global_load_dwordx4 v[132:135], v[18:19], off offset:1024
	global_load_dwordx4 v[136:139], v[18:19], off offset:2048
	global_load_dwordx4 v[140:143], v[18:19], off offset:3072
	s_add_i32 s12, s12, s8
	s_cmp_gt_i32 s12, 0x2bff
	s_cselect_b32 s98, 0, s6
	s_cselect_b32 s99, 0, s7
	v_lshl_add_u64 v[26:27], v[18:19], 0, s[98:99]
	global_load_dwordx4 v[144:147], v[26:27], off
	global_load_dwordx4 v[148:151], v[26:27], off offset:1024
	global_load_dwordx4 v[152:155], v[26:27], off offset:2048
	global_load_dwordx4 v[156:159], v[26:27], off offset:3072
	s_add_i32 s12, s12, s8
	s_cmp_gt_i32 s12, 0x2bff
	s_cselect_b32 s98, 0, s6
	s_cselect_b32 s99, 0, s7
	v_lshl_add_u64 v[28:29], v[26:27], 0, s[98:99]
	global_load_dwordx4 v[160:163], v[28:29], off
	global_load_dwordx4 v[164:167], v[28:29], off offset:1024
	global_load_dwordx4 v[168:171], v[28:29], off offset:2048
	global_load_dwordx4 v[172:175], v[28:29], off offset:3072
	s_add_i32 s12, s12, s8
	s_cmp_gt_i32 s12, 0x2bff
	s_cselect_b32 s98, 0, s6
	s_cselect_b32 s99, 0, s7
	v_lshl_add_u64 v[30:31], v[28:29], 0, s[98:99]
	global_load_dwordx4 v[176:179], v[30:31], off
	global_load_dwordx4 v[180:183], v[30:31], off offset:1024
	global_load_dwordx4 v[184:187], v[30:31], off offset:2048
	global_load_dwordx4 v[188:191], v[30:31], off offset:3072
	s_add_i32 s12, s12, s8
	s_cmp_gt_i32 s12, 0x2bff
	s_cselect_b32 s98, 0, s6
	s_cselect_b32 s99, 0, s7
	v_lshl_add_u64 v[32:33], v[30:31], 0, s[98:99]
	global_load_dwordx4 v[64:67], v[32:33], off
	global_load_dwordx4 v[68:71], v[32:33], off offset:1024
	global_load_dwordx4 v[72:75], v[32:33], off offset:2048
	global_load_dwordx4 v[76:79], v[32:33], off offset:3072
	s_add_i32 s12, s12, s8
	s_cmp_gt_i32 s12, 0x2bff
	s_cselect_b32 s98, 0, s6
	s_cselect_b32 s99, 0, s7
	v_lshl_add_u64 v[34:35], v[32:33], 0, s[98:99]
	global_load_dwordx4 v[80:83], v[34:35], off
	global_load_dwordx4 v[84:87], v[34:35], off offset:1024
	global_load_dwordx4 v[88:91], v[34:35], off offset:2048
	global_load_dwordx4 v[92:95], v[34:35], off offset:3072
	s_waitcnt vmcnt(20)
	v_lshlrev_b32_e32 v36, 16, v128
	v_and_b32_e32 v128, 0xffff0000, v128
	v_lshlrev_b32_e32 v37, 16, v129
	v_and_b32_e32 v129, 0xffff0000, v129
	v_lshlrev_b32_e32 v38, 16, v130
	v_and_b32_e32 v130, 0xffff0000, v130
	v_lshlrev_b32_e32 v39, 16, v131
	v_and_b32_e32 v131, 0xffff0000, v131
	v_mul_f32_e32 v128, v97, v128
	v_mul_f32_e32 v129, v99, v129
	v_mul_f32_e32 v130, v101, v130
	v_mul_f32_e32 v131, v103, v131
	v_fmac_f32_e32 v128, v96, v36
	v_fmac_f32_e32 v129, v98, v37
	v_fmac_f32_e32 v130, v100, v38
	v_fmac_f32_e32 v131, v102, v39
	v_add_f32_e32 v40, v128, v129
	v_add_f32_e32 v40, v130, v40
	v_add_f32_e32 v40, v131, v40
	v_add_f32_e32 v20, 0, v40
	v_lshlrev_b32_e32 v36, 16, v132
	v_and_b32_e32 v132, 0xffff0000, v132
	v_lshlrev_b32_e32 v37, 16, v133
	v_and_b32_e32 v133, 0xffff0000, v133
	v_lshlrev_b32_e32 v38, 16, v134
	v_and_b32_e32 v134, 0xffff0000, v134
	v_lshlrev_b32_e32 v39, 16, v135
	v_and_b32_e32 v135, 0xffff0000, v135
	v_mul_f32_e32 v132, v105, v132
	v_mul_f32_e32 v133, v107, v133
	v_mul_f32_e32 v134, v109, v134
	v_mul_f32_e32 v135, v111, v135
	v_fmac_f32_e32 v132, v104, v36
	v_fmac_f32_e32 v133, v106, v37
	v_fmac_f32_e32 v134, v108, v38
	v_fmac_f32_e32 v135, v110, v39
	v_add_f32_e32 v40, v132, v133
	v_add_f32_e32 v40, v134, v40
	v_add_f32_e32 v40, v135, v40
	v_add_f32_e32 v20, v20, v40
	v_lshlrev_b32_e32 v36, 16, v136
	v_and_b32_e32 v136, 0xffff0000, v136
	v_lshlrev_b32_e32 v37, 16, v137
	v_and_b32_e32 v137, 0xffff0000, v137
	v_lshlrev_b32_e32 v38, 16, v138
	v_and_b32_e32 v138, 0xffff0000, v138
	v_lshlrev_b32_e32 v39, 16, v139
	v_and_b32_e32 v139, 0xffff0000, v139
	v_mul_f32_e32 v136, v113, v136
	v_mul_f32_e32 v137, v115, v137
	v_mul_f32_e32 v138, v117, v138
	v_mul_f32_e32 v139, v119, v139
	v_fmac_f32_e32 v136, v112, v36
	v_fmac_f32_e32 v137, v114, v37
	v_fmac_f32_e32 v138, v116, v38
	v_fmac_f32_e32 v139, v118, v39
	v_add_f32_e32 v40, v136, v137
	v_add_f32_e32 v40, v138, v40
	v_add_f32_e32 v40, v139, v40
	v_add_f32_e32 v20, v20, v40
	v_lshlrev_b32_e32 v36, 16, v140
	v_and_b32_e32 v140, 0xffff0000, v140
	v_lshlrev_b32_e32 v37, 16, v141
	v_and_b32_e32 v141, 0xffff0000, v141
	v_lshlrev_b32_e32 v38, 16, v142
	v_and_b32_e32 v142, 0xffff0000, v142
	v_lshlrev_b32_e32 v39, 16, v143
	v_and_b32_e32 v143, 0xffff0000, v143
	v_mul_f32_e32 v140, v121, v140
	v_mul_f32_e32 v141, v123, v141
	v_mul_f32_e32 v142, v125, v142
	v_mul_f32_e32 v143, v127, v143
	v_fmac_f32_e32 v140, v120, v36
	v_fmac_f32_e32 v141, v122, v37
	v_fmac_f32_e32 v142, v124, v38
	v_fmac_f32_e32 v143, v126, v39
	v_add_f32_e32 v40, v140, v141
	v_add_f32_e32 v40, v142, v40
	v_add_f32_e32 v40, v143, v40
	v_add_f32_e32 v20, v20, v40
	s_waitcnt vmcnt(16)
	v_lshlrev_b32_e32 v36, 16, v144
	v_and_b32_e32 v144, 0xffff0000, v144
	v_lshlrev_b32_e32 v37, 16, v145
	v_and_b32_e32 v145, 0xffff0000, v145
	v_lshlrev_b32_e32 v38, 16, v146
	v_and_b32_e32 v146, 0xffff0000, v146
	v_lshlrev_b32_e32 v39, 16, v147
	v_and_b32_e32 v147, 0xffff0000, v147
	v_mul_f32_e32 v144, v97, v144
	v_mul_f32_e32 v145, v99, v145
	v_mul_f32_e32 v146, v101, v146
	v_mul_f32_e32 v147, v103, v147
	v_fmac_f32_e32 v144, v96, v36
	v_fmac_f32_e32 v145, v98, v37
	v_fmac_f32_e32 v146, v100, v38
	v_fmac_f32_e32 v147, v102, v39
	v_add_f32_e32 v40, v144, v145
	v_add_f32_e32 v40, v146, v40
	v_add_f32_e32 v40, v147, v40
	v_add_f32_e32 v21, 0, v40
	v_lshlrev_b32_e32 v36, 16, v148
	v_and_b32_e32 v148, 0xffff0000, v148
	v_lshlrev_b32_e32 v37, 16, v149
	v_and_b32_e32 v149, 0xffff0000, v149
	v_lshlrev_b32_e32 v38, 16, v150
	v_and_b32_e32 v150, 0xffff0000, v150
	v_lshlrev_b32_e32 v39, 16, v151
	v_and_b32_e32 v151, 0xffff0000, v151
	v_mul_f32_e32 v148, v105, v148
	v_mul_f32_e32 v149, v107, v149
	v_mul_f32_e32 v150, v109, v150
	v_mul_f32_e32 v151, v111, v151
	v_fmac_f32_e32 v148, v104, v36
	v_fmac_f32_e32 v149, v106, v37
	v_fmac_f32_e32 v150, v108, v38
	v_fmac_f32_e32 v151, v110, v39
	v_add_f32_e32 v40, v148, v149
	v_add_f32_e32 v40, v150, v40
	v_add_f32_e32 v40, v151, v40
	v_add_f32_e32 v21, v21, v40
	v_lshlrev_b32_e32 v36, 16, v152
	v_and_b32_e32 v152, 0xffff0000, v152
	v_lshlrev_b32_e32 v37, 16, v153
	v_and_b32_e32 v153, 0xffff0000, v153
	v_lshlrev_b32_e32 v38, 16, v154
	v_and_b32_e32 v154, 0xffff0000, v154
	v_lshlrev_b32_e32 v39, 16, v155
	v_and_b32_e32 v155, 0xffff0000, v155
	v_mul_f32_e32 v152, v113, v152
	v_mul_f32_e32 v153, v115, v153
	v_mul_f32_e32 v154, v117, v154
	v_mul_f32_e32 v155, v119, v155
	v_fmac_f32_e32 v152, v112, v36
	v_fmac_f32_e32 v153, v114, v37
	v_fmac_f32_e32 v154, v116, v38
	v_fmac_f32_e32 v155, v118, v39
	v_add_f32_e32 v40, v152, v153
	v_add_f32_e32 v40, v154, v40
	v_add_f32_e32 v40, v155, v40
	v_add_f32_e32 v21, v21, v40
	v_lshlrev_b32_e32 v36, 16, v156
	v_and_b32_e32 v156, 0xffff0000, v156
	v_lshlrev_b32_e32 v37, 16, v157
	v_and_b32_e32 v157, 0xffff0000, v157
	v_lshlrev_b32_e32 v38, 16, v158
	v_and_b32_e32 v158, 0xffff0000, v158
	v_lshlrev_b32_e32 v39, 16, v159
	v_and_b32_e32 v159, 0xffff0000, v159
	v_mul_f32_e32 v156, v121, v156
	v_mul_f32_e32 v157, v123, v157
	v_mul_f32_e32 v158, v125, v158
	v_mul_f32_e32 v159, v127, v159
	v_fmac_f32_e32 v156, v120, v36
	v_fmac_f32_e32 v157, v122, v37
	v_fmac_f32_e32 v158, v124, v38
	v_fmac_f32_e32 v159, v126, v39
	v_add_f32_e32 v40, v156, v157
	v_add_f32_e32 v40, v158, v40
	v_add_f32_e32 v40, v159, v40
	v_add_f32_e32 v21, v21, v40
	s_waitcnt vmcnt(12)
	v_lshlrev_b32_e32 v36, 16, v160
	v_and_b32_e32 v160, 0xffff0000, v160
	v_lshlrev_b32_e32 v37, 16, v161
	v_and_b32_e32 v161, 0xffff0000, v161
	v_lshlrev_b32_e32 v38, 16, v162
	v_and_b32_e32 v162, 0xffff0000, v162
	v_lshlrev_b32_e32 v39, 16, v163
	v_and_b32_e32 v163, 0xffff0000, v163
	v_mul_f32_e32 v160, v97, v160
	v_mul_f32_e32 v161, v99, v161
	v_mul_f32_e32 v162, v101, v162
	v_mul_f32_e32 v163, v103, v163
	v_fmac_f32_e32 v160, v96, v36
	v_fmac_f32_e32 v161, v98, v37
	v_fmac_f32_e32 v162, v100, v38
	v_fmac_f32_e32 v163, v102, v39
	v_add_f32_e32 v40, v160, v161
	v_add_f32_e32 v40, v162, v40
	v_add_f32_e32 v40, v163, v40
	v_add_f32_e32 v22, 0, v40
	v_lshlrev_b32_e32 v36, 16, v164
	v_and_b32_e32 v164, 0xffff0000, v164
	v_lshlrev_b32_e32 v37, 16, v165
	v_and_b32_e32 v165, 0xffff0000, v165
	v_lshlrev_b32_e32 v38, 16, v166
	v_and_b32_e32 v166, 0xffff0000, v166
	v_lshlrev_b32_e32 v39, 16, v167
	v_and_b32_e32 v167, 0xffff0000, v167
	v_mul_f32_e32 v164, v105, v164
	v_mul_f32_e32 v165, v107, v165
	v_mul_f32_e32 v166, v109, v166
	v_mul_f32_e32 v167, v111, v167
	v_fmac_f32_e32 v164, v104, v36
	v_fmac_f32_e32 v165, v106, v37
	v_fmac_f32_e32 v166, v108, v38
	v_fmac_f32_e32 v167, v110, v39
	v_add_f32_e32 v40, v164, v165
	v_add_f32_e32 v40, v166, v40
	v_add_f32_e32 v40, v167, v40
	v_add_f32_e32 v22, v22, v40
	v_lshlrev_b32_e32 v36, 16, v168
	v_and_b32_e32 v168, 0xffff0000, v168
	v_lshlrev_b32_e32 v37, 16, v169
	v_and_b32_e32 v169, 0xffff0000, v169
	v_lshlrev_b32_e32 v38, 16, v170
	v_and_b32_e32 v170, 0xffff0000, v170
	v_lshlrev_b32_e32 v39, 16, v171
	v_and_b32_e32 v171, 0xffff0000, v171
	v_mul_f32_e32 v168, v113, v168
	v_mul_f32_e32 v169, v115, v169
	v_mul_f32_e32 v170, v117, v170
	v_mul_f32_e32 v171, v119, v171
	v_fmac_f32_e32 v168, v112, v36
	v_fmac_f32_e32 v169, v114, v37
	v_fmac_f32_e32 v170, v116, v38
	v_fmac_f32_e32 v171, v118, v39
	v_add_f32_e32 v40, v168, v169
	v_add_f32_e32 v40, v170, v40
	v_add_f32_e32 v40, v171, v40
	v_add_f32_e32 v22, v22, v40
	v_lshlrev_b32_e32 v36, 16, v172
	v_and_b32_e32 v172, 0xffff0000, v172
	v_lshlrev_b32_e32 v37, 16, v173
	v_and_b32_e32 v173, 0xffff0000, v173
	v_lshlrev_b32_e32 v38, 16, v174
	v_and_b32_e32 v174, 0xffff0000, v174
	v_lshlrev_b32_e32 v39, 16, v175
	v_and_b32_e32 v175, 0xffff0000, v175
	v_mul_f32_e32 v172, v121, v172
	v_mul_f32_e32 v173, v123, v173
	v_mul_f32_e32 v174, v125, v174
	v_mul_f32_e32 v175, v127, v175
	v_fmac_f32_e32 v172, v120, v36
	v_fmac_f32_e32 v173, v122, v37
	v_fmac_f32_e32 v174, v124, v38
	v_fmac_f32_e32 v175, v126, v39
	v_add_f32_e32 v40, v172, v173
	v_add_f32_e32 v40, v174, v40
	v_add_f32_e32 v40, v175, v40
	v_add_f32_e32 v22, v22, v40
	s_waitcnt vmcnt(8)
	v_lshlrev_b32_e32 v36, 16, v176
	v_and_b32_e32 v176, 0xffff0000, v176
	v_lshlrev_b32_e32 v37, 16, v177
	v_and_b32_e32 v177, 0xffff0000, v177
	v_lshlrev_b32_e32 v38, 16, v178
	v_and_b32_e32 v178, 0xffff0000, v178
	v_lshlrev_b32_e32 v39, 16, v179
	v_and_b32_e32 v179, 0xffff0000, v179
	v_mul_f32_e32 v176, v97, v176
	v_mul_f32_e32 v177, v99, v177
	v_mul_f32_e32 v178, v101, v178
	v_mul_f32_e32 v179, v103, v179
	v_fmac_f32_e32 v176, v96, v36
	v_fmac_f32_e32 v177, v98, v37
	v_fmac_f32_e32 v178, v100, v38
	v_fmac_f32_e32 v179, v102, v39
	v_add_f32_e32 v40, v176, v177
	v_add_f32_e32 v40, v178, v40
	v_add_f32_e32 v40, v179, v40
	v_add_f32_e32 v23, 0, v40
	v_lshlrev_b32_e32 v36, 16, v180
	v_and_b32_e32 v180, 0xffff0000, v180
	v_lshlrev_b32_e32 v37, 16, v181
	v_and_b32_e32 v181, 0xffff0000, v181
	v_lshlrev_b32_e32 v38, 16, v182
	v_and_b32_e32 v182, 0xffff0000, v182
	v_lshlrev_b32_e32 v39, 16, v183
	v_and_b32_e32 v183, 0xffff0000, v183
	v_mul_f32_e32 v180, v105, v180
	v_mul_f32_e32 v181, v107, v181
	v_mul_f32_e32 v182, v109, v182
	v_mul_f32_e32 v183, v111, v183
	v_fmac_f32_e32 v180, v104, v36
	v_fmac_f32_e32 v181, v106, v37
	v_fmac_f32_e32 v182, v108, v38
	v_fmac_f32_e32 v183, v110, v39
	v_add_f32_e32 v40, v180, v181
	v_add_f32_e32 v40, v182, v40
	v_add_f32_e32 v40, v183, v40
	v_add_f32_e32 v23, v23, v40
	v_lshlrev_b32_e32 v36, 16, v184
	v_and_b32_e32 v184, 0xffff0000, v184
	v_lshlrev_b32_e32 v37, 16, v185
	v_and_b32_e32 v185, 0xffff0000, v185
	v_lshlrev_b32_e32 v38, 16, v186
	v_and_b32_e32 v186, 0xffff0000, v186
	v_lshlrev_b32_e32 v39, 16, v187
	v_and_b32_e32 v187, 0xffff0000, v187
	v_mul_f32_e32 v184, v113, v184
	v_mul_f32_e32 v185, v115, v185
	v_mul_f32_e32 v186, v117, v186
	v_mul_f32_e32 v187, v119, v187
	v_fmac_f32_e32 v184, v112, v36
	v_fmac_f32_e32 v185, v114, v37
	v_fmac_f32_e32 v186, v116, v38
	v_fmac_f32_e32 v187, v118, v39
	v_add_f32_e32 v40, v184, v185
	v_add_f32_e32 v40, v186, v40
	v_add_f32_e32 v40, v187, v40
	v_add_f32_e32 v23, v23, v40
	v_lshlrev_b32_e32 v36, 16, v188
	v_and_b32_e32 v188, 0xffff0000, v188
	v_lshlrev_b32_e32 v37, 16, v189
	v_and_b32_e32 v189, 0xffff0000, v189
	v_lshlrev_b32_e32 v38, 16, v190
	v_and_b32_e32 v190, 0xffff0000, v190
	v_lshlrev_b32_e32 v39, 16, v191
	v_and_b32_e32 v191, 0xffff0000, v191
	v_mul_f32_e32 v188, v121, v188
	v_mul_f32_e32 v189, v123, v189
	v_mul_f32_e32 v190, v125, v190
	v_mul_f32_e32 v191, v127, v191
	v_fmac_f32_e32 v188, v120, v36
	v_fmac_f32_e32 v189, v122, v37
	v_fmac_f32_e32 v190, v124, v38
	v_fmac_f32_e32 v191, v126, v39
	v_add_f32_e32 v40, v188, v189
	v_add_f32_e32 v40, v190, v40
	v_add_f32_e32 v40, v191, v40
	v_add_f32_e32 v23, v23, v40
	s_waitcnt vmcnt(4)
	v_lshlrev_b32_e32 v36, 16, v64
	v_and_b32_e32 v64, 0xffff0000, v64
	v_lshlrev_b32_e32 v37, 16, v65
	v_and_b32_e32 v65, 0xffff0000, v65
	v_lshlrev_b32_e32 v38, 16, v66
	v_and_b32_e32 v66, 0xffff0000, v66
	v_lshlrev_b32_e32 v39, 16, v67
	v_and_b32_e32 v67, 0xffff0000, v67
	v_mul_f32_e32 v64, v97, v64
	v_mul_f32_e32 v65, v99, v65
	v_mul_f32_e32 v66, v101, v66
	v_mul_f32_e32 v67, v103, v67
	v_fmac_f32_e32 v64, v96, v36
	v_fmac_f32_e32 v65, v98, v37
	v_fmac_f32_e32 v66, v100, v38
	v_fmac_f32_e32 v67, v102, v39
	v_add_f32_e32 v40, v64, v65
	v_add_f32_e32 v40, v66, v40
	v_add_f32_e32 v40, v67, v40
	v_add_f32_e32 v24, 0, v40
	v_lshlrev_b32_e32 v36, 16, v68
	v_and_b32_e32 v68, 0xffff0000, v68
	v_lshlrev_b32_e32 v37, 16, v69
	v_and_b32_e32 v69, 0xffff0000, v69
	v_lshlrev_b32_e32 v38, 16, v70
	v_and_b32_e32 v70, 0xffff0000, v70
	v_lshlrev_b32_e32 v39, 16, v71
	v_and_b32_e32 v71, 0xffff0000, v71
	v_mul_f32_e32 v68, v105, v68
	v_mul_f32_e32 v69, v107, v69
	v_mul_f32_e32 v70, v109, v70
	v_mul_f32_e32 v71, v111, v71
	v_fmac_f32_e32 v68, v104, v36
	v_fmac_f32_e32 v69, v106, v37
	v_fmac_f32_e32 v70, v108, v38
	v_fmac_f32_e32 v71, v110, v39
	v_add_f32_e32 v40, v68, v69
	v_add_f32_e32 v40, v70, v40
	v_add_f32_e32 v40, v71, v40
	v_add_f32_e32 v24, v24, v40
	v_lshlrev_b32_e32 v36, 16, v72
	v_and_b32_e32 v72, 0xffff0000, v72
	v_lshlrev_b32_e32 v37, 16, v73
	v_and_b32_e32 v73, 0xffff0000, v73
	v_lshlrev_b32_e32 v38, 16, v74
	v_and_b32_e32 v74, 0xffff0000, v74
	v_lshlrev_b32_e32 v39, 16, v75
	v_and_b32_e32 v75, 0xffff0000, v75
	v_mul_f32_e32 v72, v113, v72
	v_mul_f32_e32 v73, v115, v73
	v_mul_f32_e32 v74, v117, v74
	v_mul_f32_e32 v75, v119, v75
	v_fmac_f32_e32 v72, v112, v36
	v_fmac_f32_e32 v73, v114, v37
	v_fmac_f32_e32 v74, v116, v38
	v_fmac_f32_e32 v75, v118, v39
	v_add_f32_e32 v40, v72, v73
	v_add_f32_e32 v40, v74, v40
	v_add_f32_e32 v40, v75, v40
	v_add_f32_e32 v24, v24, v40
	v_lshlrev_b32_e32 v36, 16, v76
	v_and_b32_e32 v76, 0xffff0000, v76
	v_lshlrev_b32_e32 v37, 16, v77
	v_and_b32_e32 v77, 0xffff0000, v77
	v_lshlrev_b32_e32 v38, 16, v78
	v_and_b32_e32 v78, 0xffff0000, v78
	v_lshlrev_b32_e32 v39, 16, v79
	v_and_b32_e32 v79, 0xffff0000, v79
	v_mul_f32_e32 v76, v121, v76
	v_mul_f32_e32 v77, v123, v77
	v_mul_f32_e32 v78, v125, v78
	v_mul_f32_e32 v79, v127, v79
	v_fmac_f32_e32 v76, v120, v36
	v_fmac_f32_e32 v77, v122, v37
	v_fmac_f32_e32 v78, v124, v38
	v_fmac_f32_e32 v79, v126, v39
	v_add_f32_e32 v40, v76, v77
	v_add_f32_e32 v40, v78, v40
	v_add_f32_e32 v40, v79, v40
	v_add_f32_e32 v24, v24, v40
	s_waitcnt vmcnt(0)
	v_lshlrev_b32_e32 v36, 16, v80
	v_and_b32_e32 v80, 0xffff0000, v80
	v_lshlrev_b32_e32 v37, 16, v81
	v_and_b32_e32 v81, 0xffff0000, v81
	v_lshlrev_b32_e32 v38, 16, v82
	v_and_b32_e32 v82, 0xffff0000, v82
	v_lshlrev_b32_e32 v39, 16, v83
	v_and_b32_e32 v83, 0xffff0000, v83
	v_mul_f32_e32 v80, v97, v80
	v_mul_f32_e32 v81, v99, v81
	v_mul_f32_e32 v82, v101, v82
	v_mul_f32_e32 v83, v103, v83
	v_fmac_f32_e32 v80, v96, v36
	v_fmac_f32_e32 v81, v98, v37
	v_fmac_f32_e32 v82, v100, v38
	v_fmac_f32_e32 v83, v102, v39
	v_add_f32_e32 v40, v80, v81
	v_add_f32_e32 v40, v82, v40
	v_add_f32_e32 v40, v83, v40
	v_add_f32_e32 v25, 0, v40
	v_lshlrev_b32_e32 v36, 16, v84
	v_and_b32_e32 v84, 0xffff0000, v84
	v_lshlrev_b32_e32 v37, 16, v85
	v_and_b32_e32 v85, 0xffff0000, v85
	v_lshlrev_b32_e32 v38, 16, v86
	v_and_b32_e32 v86, 0xffff0000, v86
	v_lshlrev_b32_e32 v39, 16, v87
	v_and_b32_e32 v87, 0xffff0000, v87
	v_mul_f32_e32 v84, v105, v84
	v_mul_f32_e32 v85, v107, v85
	v_mul_f32_e32 v86, v109, v86
	v_mul_f32_e32 v87, v111, v87
	v_fmac_f32_e32 v84, v104, v36
	v_fmac_f32_e32 v85, v106, v37
	v_fmac_f32_e32 v86, v108, v38
	v_fmac_f32_e32 v87, v110, v39
	v_add_f32_e32 v40, v84, v85
	v_add_f32_e32 v40, v86, v40
	v_add_f32_e32 v40, v87, v40
	v_add_f32_e32 v25, v25, v40
	v_lshlrev_b32_e32 v36, 16, v88
	v_and_b32_e32 v88, 0xffff0000, v88
	v_lshlrev_b32_e32 v37, 16, v89
	v_and_b32_e32 v89, 0xffff0000, v89
	v_lshlrev_b32_e32 v38, 16, v90
	v_and_b32_e32 v90, 0xffff0000, v90
	v_lshlrev_b32_e32 v39, 16, v91
	v_and_b32_e32 v91, 0xffff0000, v91
	v_mul_f32_e32 v88, v113, v88
	v_mul_f32_e32 v89, v115, v89
	v_mul_f32_e32 v90, v117, v90
	v_mul_f32_e32 v91, v119, v91
	v_fmac_f32_e32 v88, v112, v36
	v_fmac_f32_e32 v89, v114, v37
	v_fmac_f32_e32 v90, v116, v38
	v_fmac_f32_e32 v91, v118, v39
	v_add_f32_e32 v40, v88, v89
	v_add_f32_e32 v40, v90, v40
	v_add_f32_e32 v40, v91, v40
	v_add_f32_e32 v25, v25, v40
	v_lshlrev_b32_e32 v36, 16, v92
	v_and_b32_e32 v92, 0xffff0000, v92
	v_lshlrev_b32_e32 v37, 16, v93
	v_and_b32_e32 v93, 0xffff0000, v93
	v_lshlrev_b32_e32 v38, 16, v94
	v_and_b32_e32 v94, 0xffff0000, v94
	v_lshlrev_b32_e32 v39, 16, v95
	v_and_b32_e32 v95, 0xffff0000, v95
	v_mul_f32_e32 v92, v121, v92
	v_mul_f32_e32 v93, v123, v93
	v_mul_f32_e32 v94, v125, v94
	v_mul_f32_e32 v95, v127, v95
	v_fmac_f32_e32 v92, v120, v36
	v_fmac_f32_e32 v93, v122, v37
	v_fmac_f32_e32 v94, v124, v38
	v_fmac_f32_e32 v95, v126, v39
	v_add_f32_e32 v40, v92, v93
	v_add_f32_e32 v40, v94, v40
	v_add_f32_e32 v40, v95, v40
	v_add_f32_e32 v25, v25, v40
	ds_bpermute_b32 v42, v12, v20
	ds_bpermute_b32 v43, v12, v21
	ds_bpermute_b32 v44, v12, v22
	ds_bpermute_b32 v45, v12, v23
	ds_bpermute_b32 v46, v12, v24
	ds_bpermute_b32 v47, v12, v25
	s_waitcnt lgkmcnt(0)
	v_add_f32_e32 v20, v20, v42
	v_add_f32_e32 v21, v21, v43
	v_add_f32_e32 v22, v22, v44
	v_add_f32_e32 v23, v23, v45
	v_add_f32_e32 v24, v24, v46
	v_add_f32_e32 v25, v25, v47
	ds_bpermute_b32 v42, v13, v20
	ds_bpermute_b32 v43, v13, v21
	ds_bpermute_b32 v44, v13, v22
	ds_bpermute_b32 v45, v13, v23
	ds_bpermute_b32 v46, v13, v24
	ds_bpermute_b32 v47, v13, v25
	s_waitcnt lgkmcnt(0)
	v_add_f32_e32 v20, v20, v42
	v_add_f32_e32 v21, v21, v43
	v_add_f32_e32 v22, v22, v44
	v_add_f32_e32 v23, v23, v45
	v_add_f32_e32 v24, v24, v46
	v_add_f32_e32 v25, v25, v47
	ds_bpermute_b32 v42, v14, v20
	ds_bpermute_b32 v43, v14, v21
	ds_bpermute_b32 v44, v14, v22
	ds_bpermute_b32 v45, v14, v23
	ds_bpermute_b32 v46, v14, v24
	ds_bpermute_b32 v47, v14, v25
	s_waitcnt lgkmcnt(0)
	v_add_f32_e32 v20, v20, v42
	v_add_f32_e32 v21, v21, v43
	v_add_f32_e32 v22, v22, v44
	v_add_f32_e32 v23, v23, v45
	v_add_f32_e32 v24, v24, v46
	v_add_f32_e32 v25, v25, v47
	ds_bpermute_b32 v42, v15, v20
	ds_bpermute_b32 v43, v15, v21
	ds_bpermute_b32 v44, v15, v22
	ds_bpermute_b32 v45, v15, v23
	ds_bpermute_b32 v46, v15, v24
	ds_bpermute_b32 v47, v15, v25
	s_waitcnt lgkmcnt(0)
	v_add_f32_e32 v20, v20, v42
	v_add_f32_e32 v21, v21, v43
	v_add_f32_e32 v22, v22, v44
	v_add_f32_e32 v23, v23, v45
	v_add_f32_e32 v24, v24, v46
	v_add_f32_e32 v25, v25, v47
	ds_bpermute_b32 v42, v16, v20
	ds_bpermute_b32 v43, v16, v21
	ds_bpermute_b32 v44, v16, v22
	ds_bpermute_b32 v45, v16, v23
	ds_bpermute_b32 v46, v16, v24
	ds_bpermute_b32 v47, v16, v25
	s_waitcnt lgkmcnt(0)
	v_add_f32_e32 v20, v20, v42
	v_add_f32_e32 v21, v21, v43
	v_add_f32_e32 v22, v22, v44
	v_add_f32_e32 v23, v23, v45
	v_add_f32_e32 v24, v24, v46
	v_add_f32_e32 v25, v25, v47
	ds_bpermute_b32 v42, v17, v20
	ds_bpermute_b32 v43, v17, v21
	ds_bpermute_b32 v44, v17, v22
	ds_bpermute_b32 v45, v17, v23
	ds_bpermute_b32 v46, v17, v24
	ds_bpermute_b32 v47, v17, v25
	s_waitcnt lgkmcnt(0)
	v_add_f32_e32 v20, v20, v42
	v_add_f32_e32 v21, v21, v43
	v_add_f32_e32 v22, v22, v44
	v_add_f32_e32 v23, v23, v45
	v_add_f32_e32 v24, v24, v46
	v_add_f32_e32 v25, v25, v47
	s_and_saveexec_b64 s[100:101], s[4:5]
	s_add_u32 s12, s78, s10
	s_addc_u32 s13, s79, s11
	s_mov_b32 s98, s0
	global_store_dword v1, v20, s[12:13]
	s_add_i32 s98, s98, s8
	s_cmp_gt_i32 s98, 0x2bff
	s_cbranch_scc1 .Lbu_st_done
	s_add_u32 s12, s12, s2
	s_addc_u32 s13, s13, s3
	global_store_dword v1, v21, s[12:13]
	s_add_i32 s98, s98, s8
	s_cmp_gt_i32 s98, 0x2bff
	s_cbranch_scc1 .Lbu_st_done
	s_add_u32 s12, s12, s2
	s_addc_u32 s13, s13, s3
	global_store_dword v1, v22, s[12:13]
	s_add_i32 s98, s98, s8
	s_cmp_gt_i32 s98, 0x2bff
	s_cbranch_scc1 .Lbu_st_done
	s_add_u32 s12, s12, s2
	s_addc_u32 s13, s13, s3
	global_store_dword v1, v23, s[12:13]
	s_add_i32 s98, s98, s8
	s_cmp_gt_i32 s98, 0x2bff
	s_cbranch_scc1 .Lbu_st_done
	s_add_u32 s12, s12, s2
	s_addc_u32 s13, s13, s3
	global_store_dword v1, v24, s[12:13]
	s_add_i32 s98, s98, s8
	s_cmp_gt_i32 s98, 0x2bff
	s_cbranch_scc1 .Lbu_st_done
	s_add_u32 s12, s12, s2
	s_addc_u32 s13, s13, s3
	global_store_dword v1, v25, s[12:13]
.Lbu_st_done:
	s_or_b64 exec, exec, s[100:101]
	s_mul_i32 s98, s8, 6
	s_add_i32 s0, s0, s98
	s_cmp_gt_i32 s0, 0x2bff
	s_cbranch_scc1 .LBB0_741
	s_lshl_b32 s99, s98, 2
	s_add_u32 s10, s10, s99
	s_addc_u32 s11, s11, 0
	s_mov_b32 s99, 0
	s_lshl_b64 s[98:99], s[98:99], 12
	v_lshl_add_u64 v[10:11], v[10:11], 0, s[98:99]
	s_branch .Lbu_outer

.LBB0_824:
	v_lshlrev_b32_e32 v0, 4, v0
	v_and_b32_e32 v0, 0xf0, v0
	s_add_i32 s1, 0, 0x11000
	v_add_u32_e32 v7, 0, v0
	v_add_u32_e32 v0, s1, v0
	s_add_u32 s20, s78, 0x800000
	v_readlane_b32 s1, v254, 34
	s_addc_u32 s21, s79, 0
	s_lshr_b32 s22, s1, 7
	s_movk_i32 s1, 0x110
	v_ashrrev_i32_e32 v3, 5, v1
	v_bfe_u32 v5, v1, 2, 2
	v_lshlrev_b32_e32 v11, 1, v1
	v_lshlrev_b32_e32 v13, 3, v1
	v_cmp_gt_u32_e64 s[4:5], 32, v1
	v_mul_lo_u32 v1, v2, s1
	v_mul_lo_u32 v2, v4, s1
	v_mul_lo_u32 v4, v6, s1
	v_mul_lo_u32 v6, v8, s1
	v_mul_lo_u32 v8, v10, s1
	v_mul_lo_u32 v10, v12, s1
	v_mul_lo_u32 v12, v14, s1
	v_mul_lo_u32 v14, v16, s1
	s_movk_i32 s1, 0x440
	v_lshlrev_b32_e32 v196, 3, v3
	v_lshlrev_b32_e32 v9, 4, v3
	v_lshlrev_b32_e32 v217, 2, v3
	v_and_b32_e32 v11, 32, v11
	v_mul_lo_u32 v3, v3, s1
	v_mul_u32_u24_e32 v5, 0x110, v5
	v_and_b32_e32 v13, 24, v13
	s_add_u32 s2, s78, 0x500000
	v_mul_u32_u24_e32 v15, 0x110, v34
	v_add3_u32 v3, v3, v5, v11
	v_ashrrev_i32_e32 v197, 31, v196
	s_addc_u32 s3, s79, 0
	v_add3_u32 v218, v15, v9, 0
	v_add3_u32 v219, v3, v13, 0
	v_mov_b32_e32 v199, 0
	v_add_u32_e32 v220, v7, v1
	v_add_u32_e32 v221, v0, v1
	v_add_u32_e32 v222, v7, v2
	v_add_u32_e32 v223, v0, v2
	v_add_u32_e32 v224, v7, v4
	v_add_u32_e32 v225, v0, v4
	v_add_u32_e32 v226, v7, v6
	v_add_u32_e32 v227, v0, v6
	v_add_u32_e32 v228, v7, v8
	v_add_u32_e32 v229, v0, v8
	v_add_u32_e32 v230, v7, v10
	v_add_u32_e32 v231, v0, v10
	v_add_u32_e32 v232, v7, v12
	v_add_u32_e32 v233, v0, v12
	v_add_u32_e32 v234, v7, v14
	v_add_u32_e32 v235, v0, v14
	v_lshlrev_b64 v[200:201], 1, v[18:19]
	v_lshlrev_b64 v[202:203], 1, v[20:21]
	v_lshlrev_b64 v[204:205], 1, v[22:23]
	v_lshlrev_b64 v[206:207], 1, v[24:25]
	v_lshlrev_b64 v[208:209], 1, v[26:27]
	v_lshlrev_b64 v[210:211], 1, v[28:29]
	v_lshlrev_b64 v[212:213], 1, v[30:31]
	v_lshlrev_b64 v[214:215], 1, v[32:33]
	v_mbcnt_hi_u32_b32 v236, -1, v193
	s_waitcnt vmcnt(0)
	s_branch .LBB0_827

.LBB0_827:
	v_mov_b32_e32 v237, v238
	s_ashr_i32 s10, s0, 6
	v_lshrrev_b32_e32 v198, 2, v237
	v_lshlrev_b64 v[0:1], 11, v[198:199]
	s_lshl_b32 s12, s10, 7
	v_lshl_add_u64 v[0:1], s[80:81], 0, v[0:1]
	s_ashr_i32 s13, s12, 31
	v_lshl_add_u64 v[0:1], s[12:13], 1, v[0:1]
	v_lshl_add_u64 v[0:1], v[196:197], 1, v[0:1]
	s_waitcnt lgkmcnt(0)
	global_load_dwordx4 v[160:163], v[0:1], off
	global_load_dwordx4 v[164:167], v[0:1], off offset:32
	global_load_dwordx4 v[168:171], v[0:1], off offset:64
	global_load_dwordx4 v[172:175], v[0:1], off offset:96
	global_load_dwordx4 v[176:179], v[0:1], off offset:128
	global_load_dwordx4 v[180:183], v[0:1], off offset:160
	global_load_dwordx4 v[184:187], v[0:1], off offset:192
	global_load_dwordx4 v[188:191], v[0:1], off offset:224
	v_readlane_b32 s0, v254, 0
	s_add_i32 s1, s0, s88
	s_cmp_ge_i32 s1, s18
	s_cselect_b64 s[14:15], -1, 0
	s_cmp_lt_i32 s1, s18
	v_mov_b32_e32 v239, v195
	s_mov_b32 s11, s8
	v_writelane_b32 v254, s1, 0
	s_cselect_b32 s6, s1, s0
	s_movk_i32 s1, 0x1ff
	s_mov_b32 s0, 0
	s_barrier
	ds_write_b128 v220, v[96:99]
	ds_write_b128 v221, v[100:103]
	ds_write_b128 v222, v[104:107]
	ds_write_b128 v223, v[108:111]
	ds_write_b128 v224, v[112:115]
	ds_write_b128 v225, v[116:119]
	ds_write_b128 v226, v[120:123]
	ds_write_b128 v227, v[124:127]
	ds_write_b128 v228, v[128:131]
	ds_write_b128 v229, v[132:135]
	ds_write_b128 v230, v[136:139]
	ds_write_b128 v231, v[140:143]
	ds_write_b128 v232, v[144:147]
	ds_write_b128 v233, v[148:151]
	ds_write_b128 v234, v[152:155]
	ds_write_b128 v235, v[156:159]
	s_waitcnt lgkmcnt(0)
	s_barrier
.LBB0_828:
	s_add_i32 s7, s1, s0
	s_add_i32 s7, s7, 1
	s_ashr_i32 s7, s7, 1
	s_lshl_b32 s8, s7, 2
	s_add_i32 s8, s8, 0
	s_add_i32 s8, s8, 0x22000
	v_mov_b32_e32 v0, s8
	ds_read_b32 v0, v0
	s_add_i32 s8, s7, -1
	s_waitcnt lgkmcnt(0)
	v_readfirstlane_b32 s9, v0
	s_cmp_gt_i32 s9, s6
	s_cselect_b32 s1, s8, s1
	s_cselect_b32 s0, s0, s7
	s_cmp_lt_i32 s0, s1
	s_cbranch_scc1 .LBB0_828
	s_lshl_b32 s98, s0, 2
	s_add_u32 s98, s78, s98
	s_addc_u32 s99, s79, 0
	global_load_dword v20, v199, s[98:99]
	s_lshl_b32 s1, s0, 2
	s_lshl_b32 s7, s0, 8
	s_add_i32 s1, s1, 0
	s_and_b32 s16, s7, 0x3f00
	s_add_i32 s1, s1, 0x22000
	s_lshl_b32 s7, s16, 11
	v_readlane_b32 s8, v254, 43
	v_readlane_b32 s9, v254, 44
	s_add_u32 s17, s8, s7
	s_addc_u32 s23, s9, 0
	s_lshl_b32 s8, s0, 1
	s_and_b32 s8, s8, 0xffffff80
	s_ashr_i32 s9, s8, 31
	s_lshl_b64 s[8:9], s[8:9], 1
	s_add_u32 s24, s17, s8
	s_addc_u32 s25, s23, s9
	v_readlane_b32 s26, v254, 45
	v_readlane_b32 s27, v254, 46
	s_add_u32 s7, s26, s7
	s_addc_u32 s17, s27, 0
	s_add_u32 s8, s7, s8
	v_mov_b32_e32 v195, v199
	s_addc_u32 s9, s17, s9
	v_lshl_add_u64 v[0:1], s[24:25], 0, v[194:195]
	v_lshl_add_u64 v[2:3], s[8:9], 0, v[194:195]
	v_lshl_add_u64 v[4:5], v[0:1], 0, v[200:201]
	v_lshl_add_u64 v[6:7], v[2:3], 0, v[200:201]
	global_load_dwordx4 v[96:99], v[4:5], off
	global_load_dwordx4 v[100:103], v[6:7], off
	v_lshl_add_u64 v[4:5], v[0:1], 0, v[202:203]
	v_lshl_add_u64 v[6:7], v[2:3], 0, v[202:203]
	global_load_dwordx4 v[104:107], v[4:5], off
	global_load_dwordx4 v[108:111], v[6:7], off
	v_lshl_add_u64 v[4:5], v[0:1], 0, v[204:205]
	v_lshl_add_u64 v[6:7], v[2:3], 0, v[204:205]
	global_load_dwordx4 v[112:115], v[4:5], off
	global_load_dwordx4 v[116:119], v[6:7], off
	v_lshl_add_u64 v[4:5], v[0:1], 0, v[206:207]
	v_lshl_add_u64 v[6:7], v[2:3], 0, v[206:207]
	global_load_dwordx4 v[120:123], v[4:5], off
	global_load_dwordx4 v[124:127], v[6:7], off
	v_lshl_add_u64 v[4:5], v[0:1], 0, v[208:209]
	v_lshl_add_u64 v[6:7], v[2:3], 0, v[208:209]
	global_load_dwordx4 v[128:131], v[4:5], off
	global_load_dwordx4 v[132:135], v[6:7], off
	v_lshl_add_u64 v[4:5], v[0:1], 0, v[210:211]
	v_lshl_add_u64 v[6:7], v[2:3], 0, v[210:211]
	global_load_dwordx4 v[136:139], v[4:5], off
	global_load_dwordx4 v[140:143], v[6:7], off
	v_lshl_add_u64 v[4:5], v[0:1], 0, v[212:213]
	v_lshl_add_u64 v[0:1], v[0:1], 0, v[214:215]
	v_lshl_add_u64 v[6:7], v[2:3], 0, v[212:213]
	global_load_dwordx4 v[144:147], v[4:5], off
	global_load_dwordx4 v[148:151], v[6:7], off
	v_lshl_add_u64 v[2:3], v[2:3], 0, v[214:215]
	global_load_dwordx4 v[152:155], v[0:1], off
	global_load_dwordx4 v[156:159], v[2:3], off
	v_mov_b32_e32 v0, s1
	ds_read_b32 v0, v0
	s_ashr_i32 s1, s0, 31
	s_waitcnt lgkmcnt(0)
	v_readfirstlane_b32 s7, v0
	s_sub_i32 s8, s6, s7
	s_cmp_lg_u32 s8, 0
	s_cselect_b64 s[6:7], -1, 0
	s_cmp_eq_u32 s8, 0
	s_cbranch_scc1 .LBB0_844
	s_lshl_b32 s9, s8, 8
	s_waitcnt vmcnt(16)
	v_subrev_u32_e32 v0, s9, v20
	v_add_u32_e32 v195, 0x100, v0
	s_and_b64 vcc, exec, s[6:7]
	s_cbranch_vccz .LBB0_845

.LBB0_832:
	v_add_u32_e32 v0, s16, v216
	v_lshl_or_b32 v238, v0, 2, 3

.LBB0_841:
	v_and_b32_e32 v1, 64, v236
	v_xor_b32_e32 v0, 32, v236
	v_add_u32_e32 v1, 64, v1
	v_cmp_lt_i32_e64 s[6:7], v0, v1
	v_cvt_pk_bf16_f32 v1, v82, v83
	v_cvt_pk_bf16_f32 v2, v84, v85
	v_cndmask_b32_e64 v0, v236, v0, s[6:7]
	v_lshlrev_b32_e32 v0, 2, v0
	ds_bpermute_b32 v160, v0, v240
	v_cvt_pk_bf16_f32 v0, v80, v81
	v_cvt_pk_bf16_f32 v3, v86, v87
	v_cvt_pk_bf16_f32 v4, v88, v89
	v_cvt_pk_bf16_f32 v5, v90, v91
	v_cvt_pk_bf16_f32 v6, v92, v93
	v_cvt_pk_bf16_f32 v7, v94, v95
	v_cvt_pk_bf16_f32 v8, v64, v65
	v_cvt_pk_bf16_f32 v9, v66, v67
	v_cvt_pk_bf16_f32 v10, v68, v69
	v_cvt_pk_bf16_f32 v11, v70, v71
	v_cvt_pk_bf16_f32 v12, v72, v73
	v_cvt_pk_bf16_f32 v13, v74, v75
	v_cvt_pk_bf16_f32 v14, v76, v77
	v_cvt_pk_bf16_f32 v15, v78, v79
	v_cvt_pk_bf16_f32 v16, v48, v49
	v_cvt_pk_bf16_f32 v17, v50, v51
	v_cvt_pk_bf16_f32 v18, v52, v53
	v_cvt_pk_bf16_f32 v19, v54, v55
	v_cvt_pk_bf16_f32 v20, v56, v57
	v_cvt_pk_bf16_f32 v21, v58, v59
	v_cvt_pk_bf16_f32 v22, v60, v61
	v_cvt_pk_bf16_f32 v23, v62, v63
	v_cvt_pk_bf16_f32 v24, v32, v33
	v_cvt_pk_bf16_f32 v25, v34, v35
	v_cvt_pk_bf16_f32 v26, v36, v37
	v_cvt_pk_bf16_f32 v27, v38, v39
	v_cvt_pk_bf16_f32 v28, v40, v41
	v_cvt_pk_bf16_f32 v29, v42, v43
	v_cvt_pk_bf16_f32 v30, v44, v45
	v_cvt_pk_bf16_f32 v31, v46, v47
	v_cmp_lt_i32_e32 vcc, v216, v239
	v_permlane32_swap_b32_e32 v0, v2
	v_permlane32_swap_b32_e32 v1, v3
	v_permlane32_swap_b32_e32 v4, v6
	v_permlane32_swap_b32_e32 v5, v7
	v_permlane32_swap_b32_e32 v8, v10
	v_permlane32_swap_b32_e32 v9, v11
	v_permlane32_swap_b32_e32 v12, v14
	v_permlane32_swap_b32_e32 v13, v15
	v_permlane32_swap_b32_e32 v16, v18
	v_permlane32_swap_b32_e32 v17, v19
	v_permlane32_swap_b32_e32 v20, v22
	v_permlane32_swap_b32_e32 v21, v23
	v_permlane32_swap_b32_e32 v24, v26
	v_permlane32_swap_b32_e32 v25, v27
	v_permlane32_swap_b32_e32 v28, v30
	v_permlane32_swap_b32_e32 v29, v31
	s_and_saveexec_b64 s[6:7], vcc
	s_cbranch_execz .Latt_w0
	v_and_b32_e32 v32, 3, v237
	v_lshl_or_b32 v198, v198, 2, v32
	v_lshlrev_b64 v[32:33], 11, v[198:199]
	v_lshl_add_u64 v[32:33], s[76:77], 0, v[32:33]
	v_lshl_add_u64 v[32:33], s[12:13], 1, v[32:33]
	v_lshl_add_u64 v[32:33], v[196:197], 1, v[32:33]
	global_store_dwordx4 v[32:33], v[0:3], off
	global_store_dwordx4 v[32:33], v[4:7], off offset:32
	global_store_dwordx4 v[32:33], v[8:11], off offset:64
	global_store_dwordx4 v[32:33], v[12:15], off offset:96
	global_store_dwordx4 v[32:33], v[16:19], off offset:128
	global_store_dwordx4 v[32:33], v[20:23], off offset:160
	global_store_dwordx4 v[32:33], v[24:27], off offset:192
	global_store_dwordx4 v[32:33], v[28:31], off offset:224
	s_and_b64 exec, exec, s[4:5]
	s_cbranch_execz .Latt_w8
	v_lshlrev_b64 v[0:1], 5, v[198:199]
	v_lshl_add_u64 v[0:1], s[2:3], 0, v[0:1]
	s_ashr_i32 s11, s10, 31
	s_waitcnt lgkmcnt(0)
	v_add_f32_e32 v2, v240, v160
	v_lshl_add_u64 v[0:1], s[10:11], 2, v[0:1]
	global_store_dword v[0:1], v2, off
	s_waitcnt vmcnt(9)
	s_branch .LBB0_825
.LBB0_844:
	v_mov_b32_e32 v195, 0x100
	s_waitcnt vmcnt(16)
	s_and_b64 vcc, exec, s[6:7]
	s_cbranch_vccnz .LBB0_831

.Latt_skip:
	s_waitcnt vmcnt(0)
	s_branch .LBB0_826

.Latt_w8:
	s_waitcnt vmcnt(8)
	s_branch .LBB0_825

	.amdhsa_kernel _Z14fwd_megakernel6Params
		.amdhsa_group_segment_fixed_size 0
		.amdhsa_private_segment_fixed_size 0
		.amdhsa_kernarg_size 432
		.amdhsa_user_sgpr_count 2
		.amdhsa_user_sgpr_dispatch_ptr 0
		.amdhsa_user_sgpr_queue_ptr 0
		.amdhsa_user_sgpr_kernarg_segment_ptr 1
		.amdhsa_user_sgpr_dispatch_id 0
		.amdhsa_user_sgpr_kernarg_preload_length 0
		.amdhsa_user_sgpr_kernarg_preload_offset 0
		.amdhsa_user_sgpr_private_segment_size 0
		.amdhsa_uses_dynamic_stack 0
		.amdhsa_enable_private_segment 0
		.amdhsa_system_sgpr_workgroup_id_x 1
		.amdhsa_system_sgpr_workgroup_id_y 0
		.amdhsa_system_sgpr_workgroup_id_z 0
		.amdhsa_system_sgpr_workgroup_info 0
		.amdhsa_system_vgpr_workitem_id 2
		.amdhsa_next_free_vgpr 256
		.amdhsa_next_free_sgpr 102
		.amdhsa_accum_offset 256
		.amdhsa_reserve_vcc 1
		.amdhsa_float_round_mode_32 0
		.amdhsa_float_round_mode_16_64 0
		.amdhsa_float_denorm_mode_32 3
		.amdhsa_float_denorm_mode_16_64 3
		.amdhsa_dx10_clamp 1
		.amdhsa_ieee_mode 1
		.amdhsa_fp16_overflow 0
		.amdhsa_tg_split 0
		.amdhsa_exception_fp_ieee_invalid_op 0
		.amdhsa_exception_fp_denorm_src 0
		.amdhsa_exception_fp_ieee_div_zero 0
		.amdhsa_exception_fp_ieee_overflow 0
		.amdhsa_exception_fp_ieee_underflow 0
		.amdhsa_exception_fp_ieee_inexact 0
		.amdhsa_exception_int_div_zero 0
	.end_amdhsa_kernel

amdhsa.kernels:
  - .agpr_count:     0
    .args:
      - .offset:         0
        .size:           176
        .value_kind:     by_value
      - .offset:         176
        .size:           4
        .value_kind:     hidden_block_count_x
      - .offset:         180
        .size:           4
        .value_kind:     hidden_block_count_y
      - .offset:         184
        .size:           4
        .value_kind:     hidden_block_count_z
      - .offset:         188
        .size:           2
        .value_kind:     hidden_group_size_x
      - .offset:         190
        .size:           2
        .value_kind:     hidden_group_size_y
      - .offset:         192
        .size:           2
        .value_kind:     hidden_group_size_z
      - .offset:         194
        .size:           2
        .value_kind:     hidden_remainder_x
      - .offset:         196
        .size:           2
        .value_kind:     hidden_remainder_y
      - .offset:         198
        .size:           2
        .value_kind:     hidden_remainder_z
      - .offset:         216
        .size:           8
        .value_kind:     hidden_global_offset_x
      - .offset:         224
        .size:           8
        .value_kind:     hidden_global_offset_y
      - .offset:         232
        .size:           8
        .value_kind:     hidden_global_offset_z
      - .offset:         240
        .size:           2
        .value_kind:     hidden_grid_dims
      - .offset:         264
        .size:           8
        .value_kind:     hidden_multigrid_sync_arg
      - .offset:         296
        .size:           4
        .value_kind:     hidden_dynamic_lds_size
    .group_segment_fixed_size: 0
    .kernarg_segment_align: 8
    .kernarg_segment_size: 432
    .language:       OpenCL C
    .language_version:
      - 2
      - 0
    .max_flat_workgroup_size: 512
    .name:           _Z14fwd_megakernel6Params
    .private_segment_fixed_size: 0
    .sgpr_count:     108
    .sgpr_spill_count: 85
    .symbol:         _Z14fwd_megakernel6Params.kd
    .uniform_work_group_size: 1
    .uses_dynamic_stack: false
    .vgpr_count:     256
    .vgpr_spill_count: 0
    .wavefront_size: 64
